# stack: P5 rewrite + P3 staging/DPP + GEMM first-K-iteration peel (accumulator clears folded into C=0 MFMAs) + GLA stage-0 chunk load prefetch
# speedup vs baseline: 1.0138x; 1.0030x over previous
; #define PG8_STAGE(bufoff, gbase, voff) do { _Pragma("unroll") for (int _i = 0; _i < 2; ++_i) \
;         __builtin_amdgcn_global_load_lds((const unsigned*)((const char*)(gbase) + (voff)[_i]), (LAS unsigned*)(lds + (bufoff) + ldsw + _i * 8192), 16, 0, 0); } while (0)
; #define PG8_LDA(dst, b, h) do { _Pragma("unroll") for (int m = 0; m < 4; ++m) _Pragma("unroll") for (int k = 0; k < 2; ++k) dst[m][k] = *(const LAS bf16x8*)(lds + PG8_SA(b, h) + aoff + m * 2048 + k * 1024); } while (0)
; #define PG8_LDB(dst, b, h) do { _Pragma("unroll") for (int n = 0; n < 2; ++n) _Pragma("unroll") for (int k = 0; k < 2; ++k) dst[n][k] = *(const LAS bf16x8*)(lds + PG8_SB(b, h) + boff + n * 2048 + k * 1024); } while (0)
; #define PG8_MMA(ai, bj, At, Bt) do { __builtin_amdgcn_s_setprio(1); _Pragma("unroll") for (int m = 0; m < 4; ++m) _Pragma("unroll") for (int n = 0; n < 2; ++n) _Pragma("unroll") for (int k = 0; k < 2; ++k) \
;         acc[ai][bj][m][n] = __builtin_amdgcn_mfma_f32_16x16x32_bf16(Bt[n][k], At[m][k], acc[ai][bj][m][n], 0, 0, 0); __builtin_amdgcn_s_setprio(0); } while (0)
; #define PG8_BAR __builtin_amdgcn_s_barrier()
; template <class Epi, bool ALIGN_EPI, class Hook = NoHook>
; __device__ __forceinline__ void gemm_phase(LAS unsigned char* lds, const Gemm g, const StaticOrder& S, const Epi& E, const Hook& HK = Hook()) {
;     ...
;         const bool has_next = S.next(ui + 1, nxt);
;         const char* nA = has_next ? (const char*)g.A + (size_t)nxt.pm * tstepA : cA; const char* nB = has_next ? (const char*)g.Bt + (size_t)nxt.pn * tstepB : cB;
;         for (int t = 0; t < nt; t += 2) {
;             if (Hook::AT > 0 && t == Hook::AT) HK(acc, cur, wr, wc, fr, fq);
;             const bool last = (t == nt - 2);
;             const char* a1 = cA + (size_t)(t + 1) * kstep;
;             const char* a2 = last ? nA : cA + (size_t)(t + 2) * kstep; const char* b2 = last ? nB : cB + (size_t)(t + 2) * kstep;
;             const char* a3 = a2 + kstep; const char* b3 = b2 + kstep;
;             PG8_LDB(B0, 0, 0); PG8_LDB(B1, 0, 1); PG8_SCHED; PG8_LDA(At, 0, 0); PG8_STAGE(PG8_SA(1, 1), a1 + hstepA, voffA);
;             PG8_WAIT_V(8); PG8_WAIT_L(0); PG8_BAR; PG8_MMA(0, 0, At, B0); PG8_MMA(0, 1, At, B1); PG8_BAR; PG8_SCHED;
;             PG8_LDA(At, 0, 1); PG8_STAGE(PG8_SB(0, 0), b2, voffB); PG8_STAGE(PG8_SB(0, 1), b2 + hstepB, voffB); PG8_STAGE(PG8_SA(0, 0), a2, voffA);
.LBB0_47:
	s_ashr_i32 s25, s24, 31
	s_lshl_b64 s[26:27], s[24:25], 20
	s_add_u32 s28, s48, s26
	s_addc_u32 s29, s49, s27
	s_and_b64 s[26:27], s[0:1], exec
	s_cselect_b32 s7, s29, s85
	s_cselect_b32 s25, s28, s84
	s_ashr_i32 s19, s18, 31
	s_lshl_b64 s[26:27], s[18:19], 20
	s_add_u32 s76, s66, s26
	s_addc_u32 s77, s67, s27
	s_and_b64 s[26:27], s[0:1], exec
	s_cselect_b32 s19, s77, s87
	s_cselect_b32 s26, s76, s86
	s_add_u32 s84, s84, 0x80080
	s_addc_u32 s85, s85, 0
	s_add_u32 s27, s86, 0x100
	s_addc_u32 vcc_lo, s87, 0
	s_mov_b32 vcc_hi, -2
	ds_read_b128 v[152:155], v156
	ds_read_b128 v[160:163], v156 offset:1024
	ds_read_b128 v[168:171], v156 offset:2048
	ds_read_b128 v[172:175], v156 offset:3072
	ds_read_b128 v[176:179], v157
	ds_read_b128 v[180:183], v157 offset:1024
	ds_read_b128 v[184:187], v157 offset:2048
	ds_read_b128 v[188:191], v157 offset:3072
	s_add_u32 s34, s84, 0xfff80080
	s_addc_u32 s35, s85, -1
	s_cmp_eq_u32 vcc_hi, 28
	s_cselect_b32 s89, s7, s35
	s_cselect_b32 s88, s25, s34
	s_cselect_b32 s87, s19, vcc_lo
	s_cselect_b32 s86, s26, s27
	v_lshl_add_u64 v[164:165], s[84:85], 0, v[144:145]
	s_add_i32 m0, s71, 0xc000
	ds_read_b128 v[192:195], v158
	ds_read_b128 v[196:199], v158 offset:1024
	ds_read_b128 v[204:207], v158 offset:2048
	ds_read_b128 v[208:211], v158 offset:3072
	ds_read_b128 v[212:215], v158 offset:4096
	ds_read_b128 v[216:219], v158 offset:5120
	ds_read_b128 v[220:223], v158 offset:6144
	ds_read_b128 v[224:227], v158 offset:7168
	global_load_lds_dwordx4 v[164:165], off
	v_lshl_add_u64 v[164:165], s[84:85], 0, v[146:147]
	s_add_i32 m0, s71, 0xe000
	s_nop 0
	global_load_lds_dwordx4 v[164:165], off
	s_waitcnt vmcnt(8)
	s_waitcnt lgkmcnt(0)
	s_barrier
	s_setprio 1
	s_waitcnt lgkmcnt(0)
	v_mfma_f32_16x16x32_bf16 v[124:127], v[152:155], v[192:195], 0
	v_mfma_f32_16x16x32_bf16 v[120:123], v[168:171], v[192:195], 0
	v_mfma_f32_16x16x32_bf16 v[108:111], v[152:155], v[204:207], 0
	v_mfma_f32_16x16x32_bf16 v[104:107], v[168:171], v[204:207], 0
	v_mfma_f32_16x16x32_bf16 v[92:95], v[152:155], v[212:215], 0
	v_mfma_f32_16x16x32_bf16 v[88:91], v[168:171], v[212:215], 0
	v_mfma_f32_16x16x32_bf16 v[76:79], v[152:155], v[220:223], 0
	v_mfma_f32_16x16x32_bf16 v[72:75], v[168:171], v[220:223], 0
	v_mfma_f32_16x16x32_bf16 v[124:127], v[160:163], v[196:199], v[124:127]
	v_mfma_f32_16x16x32_bf16 v[120:123], v[172:175], v[196:199], v[120:123]
	v_mfma_f32_16x16x32_bf16 v[108:111], v[160:163], v[208:211], v[108:111]
	v_mfma_f32_16x16x32_bf16 v[104:107], v[172:175], v[208:211], v[104:107]
	v_mfma_f32_16x16x32_bf16 v[92:95], v[160:163], v[216:219], v[92:95]
	v_mfma_f32_16x16x32_bf16 v[88:91], v[172:175], v[216:219], v[88:91]
	v_mfma_f32_16x16x32_bf16 v[76:79], v[160:163], v[224:227], v[76:79]
	v_mfma_f32_16x16x32_bf16 v[72:75], v[172:175], v[224:227], v[72:75]
	s_setprio 0
	s_setprio 1
	v_mfma_f32_16x16x32_bf16 v[116:119], v[176:179], v[192:195], 0
	v_mfma_f32_16x16x32_bf16 v[112:115], v[184:187], v[192:195], 0
	v_mfma_f32_16x16x32_bf16 v[100:103], v[176:179], v[204:207], 0
	v_mfma_f32_16x16x32_bf16 v[96:99], v[184:187], v[204:207], 0
	v_mfma_f32_16x16x32_bf16 v[84:87], v[176:179], v[212:215], 0
	v_mfma_f32_16x16x32_bf16 v[80:83], v[184:187], v[212:215], 0
	v_mfma_f32_16x16x32_bf16 v[68:71], v[176:179], v[220:223], 0
	v_mfma_f32_16x16x32_bf16 v[64:67], v[184:187], v[220:223], 0
	v_mfma_f32_16x16x32_bf16 v[116:119], v[180:183], v[196:199], v[116:119]
	v_mfma_f32_16x16x32_bf16 v[112:115], v[188:191], v[196:199], v[112:115]
	v_mfma_f32_16x16x32_bf16 v[100:103], v[180:183], v[208:211], v[100:103]
	v_mfma_f32_16x16x32_bf16 v[96:99], v[188:191], v[208:211], v[96:99]
	v_mfma_f32_16x16x32_bf16 v[84:87], v[180:183], v[216:219], v[84:87]
	v_mfma_f32_16x16x32_bf16 v[80:83], v[188:191], v[216:219], v[80:83]
	v_mfma_f32_16x16x32_bf16 v[68:71], v[180:183], v[224:227], v[68:71]
	v_mfma_f32_16x16x32_bf16 v[64:67], v[188:191], v[224:227], v[64:67]
	s_setprio 0
	s_barrier
	s_add_i32 s34, s95, s17
	v_lshl_add_u64 v[164:165], s[86:87], 0, v[132:133]
	s_mov_b32 m0, s34
	ds_read_b128 v[192:195], v158 offset:16384
	ds_read_b128 v[196:199], v158 offset:17408
	ds_read_b128 v[204:207], v158 offset:18432
	ds_read_b128 v[208:211], v158 offset:19456
	ds_read_b128 v[212:215], v158 offset:20480
	ds_read_b128 v[216:219], v158 offset:21504
	ds_read_b128 v[220:223], v158 offset:22528
	ds_read_b128 v[224:227], v158 offset:23552
	global_load_lds_dwordx4 v[164:165], off
	s_add_i32 m0, s34, 0x2000
	s_add_u32 s34, s86, 0x80000
	v_lshl_add_u64 v[228:229], s[86:87], 0, v[128:129]
	s_addc_u32 s35, s87, 0
	s_add_i32 s64, s96, s17
	global_load_lds_dwordx4 v[228:229], off
	v_lshl_add_u64 v[230:231], s[34:35], 0, v[132:133]
	s_mov_b32 m0, s64
	v_lshl_add_u64 v[232:233], s[88:89], 0, v[130:131]
	global_load_lds_dwordx4 v[230:231], off
	v_lshl_add_u64 v[230:231], s[34:35], 0, v[128:129]
	s_add_i32 m0, s64, 0x2000
	s_nop 0
	global_load_lds_dwordx4 v[230:231], off
	v_lshl_add_u64 v[230:231], s[88:89], 0, v[134:135]
	s_mov_b32 m0, s71
	s_nop 0
	global_load_lds_dwordx4 v[230:231], off
	s_mov_b32 m0, s72
	s_nop 0
	global_load_lds_dwordx4 v[232:233], off
	s_waitcnt vmcnt(8)
	s_waitcnt lgkmcnt(0)
	s_barrier
; #define PG8_STAGE(bufoff, gbase, voff) do { _Pragma("unroll") for (int _i = 0; _i < 2; ++_i) \
;         __builtin_amdgcn_global_load_lds((const unsigned*)((const char*)(gbase) + (voff)[_i]), (LAS unsigned*)(lds + (bufoff) + ldsw + _i * 8192), 16, 0, 0); } while (0)
; #define PG8_LDA(dst, b, h) do { _Pragma("unroll") for (int m = 0; m < 4; ++m) _Pragma("unroll") for (int k = 0; k < 2; ++k) dst[m][k] = *(const LAS bf16x8*)(lds + PG8_SA(b, h) + aoff + m * 2048 + k * 1024); } while (0)
; #define PG8_LDB(dst, b, h) do { _Pragma("unroll") for (int n = 0; n < 2; ++n) _Pragma("unroll") for (int k = 0; k < 2; ++k) dst[n][k] = *(const LAS bf16x8*)(lds + PG8_SB(b, h) + boff + n * 2048 + k * 1024); } while (0)
; #define PG8_MMA(ai, bj, At, Bt) do { __builtin_amdgcn_s_setprio(1); _Pragma("unroll") for (int m = 0; m < 4; ++m) _Pragma("unroll") for (int n = 0; n < 2; ++n) _Pragma("unroll") for (int k = 0; k < 2; ++k) \
;         acc[ai][bj][m][n] = __builtin_amdgcn_mfma_f32_16x16x32_bf16(Bt[n][k], At[m][k], acc[ai][bj][m][n], 0, 0, 0); __builtin_amdgcn_s_setprio(0); } while (0)
; #define PG8_WAIT_V(n) asm volatile("s_waitcnt vmcnt(" #n ")" ::: "memory")
; #define PG8_WAIT_L(n) asm volatile("s_waitcnt lgkmcnt(" #n ")" ::: "memory")
; #define PG8_BAR __builtin_amdgcn_s_barrier()
; #define PG8_SCHED __builtin_amdgcn_sched_barrier(0)
; template <class Epi, bool ALIGN_EPI, class Hook = NoHook>
; __device__ __forceinline__ void gemm_phase(LAS unsigned char* lds, const Gemm g, const StaticOrder& S, const Epi& E, const Hook& HK = Hook()) {
;     ...
;             PG8_WAIT_V(8); PG8_WAIT_L(0); PG8_BAR; PG8_MMA(1, 0, At, B0); PG8_MMA(1, 1, At, B1); PG8_BAR; PG8_SCHED;
;             PG8_LDB(B0, 1, 0); PG8_LDB(B1, 1, 1); PG8_SCHED; PG8_LDA(At, 1, 0); PG8_STAGE(PG8_SA(0, 1), a2 + hstepA, voffA);
;             PG8_WAIT_V(8); PG8_WAIT_L(0); PG8_BAR; PG8_MMA(0, 0, At, B0); PG8_MMA(0, 1, At, B1); PG8_BAR; PG8_SCHED;
	s_setprio 1
	s_waitcnt lgkmcnt(0)
	v_mfma_f32_16x16x32_bf16 v[60:63], v[152:155], v[192:195], 0
	v_mfma_f32_16x16x32_bf16 v[56:59], v[168:171], v[192:195], 0
	v_mfma_f32_16x16x32_bf16 v[44:47], v[152:155], v[204:207], 0
	v_mfma_f32_16x16x32_bf16 v[40:43], v[168:171], v[204:207], 0
	v_mfma_f32_16x16x32_bf16 v[28:31], v[152:155], v[212:215], 0
	v_mfma_f32_16x16x32_bf16 v[24:27], v[168:171], v[212:215], 0
	v_mfma_f32_16x16x32_bf16 v[12:15], v[152:155], v[220:223], 0
	v_mfma_f32_16x16x32_bf16 v[8:11], v[168:171], v[220:223], 0
	v_mfma_f32_16x16x32_bf16 v[60:63], v[160:163], v[196:199], v[60:63]
	v_mfma_f32_16x16x32_bf16 v[56:59], v[172:175], v[196:199], v[56:59]
	v_mfma_f32_16x16x32_bf16 v[44:47], v[160:163], v[208:211], v[44:47]
	v_mfma_f32_16x16x32_bf16 v[40:43], v[172:175], v[208:211], v[40:43]
	v_mfma_f32_16x16x32_bf16 v[28:31], v[160:163], v[216:219], v[28:31]
	v_mfma_f32_16x16x32_bf16 v[24:27], v[172:175], v[216:219], v[24:27]
	v_mfma_f32_16x16x32_bf16 v[12:15], v[160:163], v[224:227], v[12:15]
	v_mfma_f32_16x16x32_bf16 v[8:11], v[172:175], v[224:227], v[8:11]
	s_setprio 0
	s_setprio 1
	v_mfma_f32_16x16x32_bf16 v[52:55], v[176:179], v[192:195], 0
	v_mfma_f32_16x16x32_bf16 v[48:51], v[184:187], v[192:195], 0
	v_mfma_f32_16x16x32_bf16 v[36:39], v[176:179], v[204:207], 0
	v_mfma_f32_16x16x32_bf16 v[32:35], v[184:187], v[204:207], 0
	v_mfma_f32_16x16x32_bf16 v[20:23], v[176:179], v[212:215], 0
	v_mfma_f32_16x16x32_bf16 v[16:19], v[184:187], v[212:215], 0
	v_mfma_f32_16x16x32_bf16 v[4:7], v[176:179], v[220:223], 0
	v_mfma_f32_16x16x32_bf16 v[0:3], v[184:187], v[220:223], 0
	v_mfma_f32_16x16x32_bf16 v[52:55], v[180:183], v[196:199], v[52:55]
	v_mfma_f32_16x16x32_bf16 v[48:51], v[188:191], v[196:199], v[48:51]
	v_mfma_f32_16x16x32_bf16 v[36:39], v[180:183], v[208:211], v[36:39]
	v_mfma_f32_16x16x32_bf16 v[32:35], v[188:191], v[208:211], v[32:35]
	v_mfma_f32_16x16x32_bf16 v[20:23], v[180:183], v[216:219], v[20:23]
	v_mfma_f32_16x16x32_bf16 v[16:19], v[188:191], v[216:219], v[16:19]
	v_mfma_f32_16x16x32_bf16 v[4:7], v[180:183], v[224:227], v[4:7]
	v_mfma_f32_16x16x32_bf16 v[0:3], v[188:191], v[224:227], v[0:3]
	s_setprio 0
	s_barrier
	s_add_i32 s64, 0, 0x18000
	v_add_u32_e32 v159, s64, v141
	s_add_i32 s52, 0, 0x1c000
	ds_read_b128 v[152:155], v159
	ds_read_b128 v[160:163], v159 offset:1024
	ds_read_b128 v[168:171], v159 offset:2048
	ds_read_b128 v[172:175], v159 offset:3072
	v_add_u32_e32 v159, s52, v141
	ds_read_b128 v[176:179], v159
	ds_read_b128 v[180:183], v159 offset:1024
	ds_read_b128 v[184:187], v159 offset:2048
	ds_read_b128 v[188:191], v159 offset:3072
	s_add_u32 s34, s88, 0x80000
	s_addc_u32 s35, s89, 0
	s_mov_b32 m0, s73
	v_lshl_add_u64 v[234:235], s[34:35], 0, v[134:135]
	ds_read_b128 v[192:195], v158 offset:32768
	ds_read_b128 v[196:199], v158 offset:33792
	ds_read_b128 v[204:207], v158 offset:34816
	ds_read_b128 v[208:211], v158 offset:35840
	ds_read_b128 v[212:215], v158 offset:36864
	ds_read_b128 v[216:219], v158 offset:37888
	ds_read_b128 v[220:223], v158 offset:38912
	ds_read_b128 v[224:227], v158 offset:39936
	global_load_lds_dwordx4 v[234:235], off
	v_lshl_add_u64 v[234:235], s[34:35], 0, v[130:131]
	s_mov_b32 m0, s83
	s_nop 0
	global_load_lds_dwordx4 v[234:235], off
	s_waitcnt vmcnt(8)
	s_waitcnt lgkmcnt(0)
	s_barrier
	s_setprio 1
	s_waitcnt lgkmcnt(0)
	v_mfma_f32_16x16x32_bf16 v[124:127], v[152:155], v[192:195], v[124:127]
	v_mfma_f32_16x16x32_bf16 v[120:123], v[168:171], v[192:195], v[120:123]
	v_mfma_f32_16x16x32_bf16 v[108:111], v[152:155], v[204:207], v[108:111]
	v_mfma_f32_16x16x32_bf16 v[104:107], v[168:171], v[204:207], v[104:107]
	v_mfma_f32_16x16x32_bf16 v[92:95], v[152:155], v[212:215], v[92:95]
	v_mfma_f32_16x16x32_bf16 v[88:91], v[168:171], v[212:215], v[88:91]
	v_mfma_f32_16x16x32_bf16 v[76:79], v[152:155], v[220:223], v[76:79]
	v_mfma_f32_16x16x32_bf16 v[72:75], v[168:171], v[220:223], v[72:75]
	v_mfma_f32_16x16x32_bf16 v[124:127], v[160:163], v[196:199], v[124:127]
	v_mfma_f32_16x16x32_bf16 v[120:123], v[172:175], v[196:199], v[120:123]
	v_mfma_f32_16x16x32_bf16 v[108:111], v[160:163], v[208:211], v[108:111]
	v_mfma_f32_16x16x32_bf16 v[104:107], v[172:175], v[208:211], v[104:107]
	v_mfma_f32_16x16x32_bf16 v[92:95], v[160:163], v[216:219], v[92:95]
	v_mfma_f32_16x16x32_bf16 v[88:91], v[172:175], v[216:219], v[88:91]
	v_mfma_f32_16x16x32_bf16 v[76:79], v[160:163], v[224:227], v[76:79]
	v_mfma_f32_16x16x32_bf16 v[72:75], v[172:175], v[224:227], v[72:75]
	s_setprio 0
	s_setprio 1
	v_mfma_f32_16x16x32_bf16 v[116:119], v[176:179], v[192:195], v[116:119]
	v_mfma_f32_16x16x32_bf16 v[112:115], v[184:187], v[192:195], v[112:115]
	v_mfma_f32_16x16x32_bf16 v[100:103], v[176:179], v[204:207], v[100:103]
	v_mfma_f32_16x16x32_bf16 v[96:99], v[184:187], v[204:207], v[96:99]
	v_mfma_f32_16x16x32_bf16 v[84:87], v[176:179], v[212:215], v[84:87]
	v_mfma_f32_16x16x32_bf16 v[80:83], v[184:187], v[212:215], v[80:83]
	v_mfma_f32_16x16x32_bf16 v[68:71], v[176:179], v[220:223], v[68:71]
	v_mfma_f32_16x16x32_bf16 v[64:67], v[184:187], v[220:223], v[64:67]
	v_mfma_f32_16x16x32_bf16 v[116:119], v[180:183], v[196:199], v[116:119]
	v_mfma_f32_16x16x32_bf16 v[112:115], v[188:191], v[196:199], v[112:115]
	v_mfma_f32_16x16x32_bf16 v[100:103], v[180:183], v[208:211], v[100:103]
	v_mfma_f32_16x16x32_bf16 v[96:99], v[188:191], v[208:211], v[96:99]
	v_mfma_f32_16x16x32_bf16 v[84:87], v[180:183], v[216:219], v[84:87]
	v_mfma_f32_16x16x32_bf16 v[80:83], v[188:191], v[216:219], v[80:83]
	v_mfma_f32_16x16x32_bf16 v[68:71], v[180:183], v[224:227], v[68:71]
	v_mfma_f32_16x16x32_bf16 v[64:67], v[188:191], v[224:227], v[64:67]
	s_setprio 0
	s_barrier
; #define PG8_STAGE(bufoff, gbase, voff) do { _Pragma("unroll") for (int _i = 0; _i < 2; ++_i) \
;         __builtin_amdgcn_global_load_lds((const unsigned*)((const char*)(gbase) + (voff)[_i]), (LAS unsigned*)(lds + (bufoff) + ldsw + _i * 8192), 16, 0, 0); } while (0)
; #define PG8_LDA(dst, b, h) do { _Pragma("unroll") for (int m = 0; m < 4; ++m) _Pragma("unroll") for (int k = 0; k < 2; ++k) dst[m][k] = *(const LAS bf16x8*)(lds + PG8_SA(b, h) + aoff + m * 2048 + k * 1024); } while (0)
; #define PG8_MMA(ai, bj, At, Bt) do { __builtin_amdgcn_s_setprio(1); _Pragma("unroll") for (int m = 0; m < 4; ++m) _Pragma("unroll") for (int n = 0; n < 2; ++n) _Pragma("unroll") for (int k = 0; k < 2; ++k) \
;         acc[ai][bj][m][n] = __builtin_amdgcn_mfma_f32_16x16x32_bf16(Bt[n][k], At[m][k], acc[ai][bj][m][n], 0, 0, 0); __builtin_amdgcn_s_setprio(0); } while (0)
; #define PG8_WAIT_V(n) asm volatile("s_waitcnt vmcnt(" #n ")" ::: "memory")
; #define PG8_WAIT_L(n) asm volatile("s_waitcnt lgkmcnt(" #n ")" ::: "memory")
; #define PG8_BAR __builtin_amdgcn_s_barrier()
; #define PG8_SCHED __builtin_amdgcn_sched_barrier(0)
; template <class Epi, bool ALIGN_EPI, class Hook = NoHook>
; __device__ __forceinline__ void gemm_phase(LAS unsigned char* lds, const Gemm g, const StaticOrder& S, const Epi& E, const Hook& HK = Hook()) {
;     ...
;             PG8_LDA(At, 1, 1); PG8_STAGE(PG8_SB(1, 0), b3, voffB); PG8_STAGE(PG8_SB(1, 1), b3 + hstepB, voffB); PG8_STAGE(PG8_SA(1, 0), a3, voffA);
;             PG8_WAIT_V(8); PG8_WAIT_L(0); PG8_BAR; PG8_MMA(1, 0, At, B0); PG8_MMA(1, 1, At, B1); PG8_BAR; PG8_SCHED;
	s_add_i32 s34, s64, s17
	v_lshl_add_u64 v[164:165], v[164:165], 0, s[12:13]
	s_mov_b32 m0, s34
	ds_read_b128 v[192:195], v158 offset:49152
	ds_read_b128 v[196:199], v158 offset:50176
	ds_read_b128 v[204:207], v158 offset:51200
	ds_read_b128 v[208:211], v158 offset:52224
	ds_read_b128 v[212:215], v158 offset:53248
	ds_read_b128 v[216:219], v158 offset:54272
	ds_read_b128 v[220:223], v158 offset:55296
	ds_read_b128 v[224:227], v158 offset:56320
	global_load_lds_dwordx4 v[164:165], off
	s_add_i32 m0, s34, 0x2000
	s_add_u32 s34, s86, 0x80080
	v_lshl_add_u64 v[164:165], v[228:229], 0, s[12:13]
	s_addc_u32 s35, s87, 0
	s_add_i32 s52, s52, s17
	global_load_lds_dwordx4 v[164:165], off
	v_lshl_add_u64 v[164:165], s[34:35], 0, v[132:133]
	s_mov_b32 m0, s52
	s_nop 0
	global_load_lds_dwordx4 v[164:165], off
	v_lshl_add_u64 v[164:165], s[34:35], 0, v[128:129]
	s_add_i32 m0, s52, 0x2000
	s_nop 0
	global_load_lds_dwordx4 v[164:165], off
	v_lshl_add_u64 v[164:165], v[230:231], 0, s[12:13]
	s_mov_b32 m0, s91
	s_nop 0
	global_load_lds_dwordx4 v[164:165], off
	v_lshl_add_u64 v[164:165], v[232:233], 0, s[12:13]
	s_mov_b32 m0, s92
	s_nop 0
	global_load_lds_dwordx4 v[164:165], off
	s_waitcnt vmcnt(8)
	s_waitcnt lgkmcnt(0)
	s_barrier
	s_setprio 1
	s_waitcnt lgkmcnt(0)
	v_mfma_f32_16x16x32_bf16 v[60:63], v[152:155], v[192:195], v[60:63]
	v_mfma_f32_16x16x32_bf16 v[56:59], v[168:171], v[192:195], v[56:59]
	v_mfma_f32_16x16x32_bf16 v[44:47], v[152:155], v[204:207], v[44:47]
	v_mfma_f32_16x16x32_bf16 v[40:43], v[168:171], v[204:207], v[40:43]
	v_mfma_f32_16x16x32_bf16 v[28:31], v[152:155], v[212:215], v[28:31]
	v_mfma_f32_16x16x32_bf16 v[24:27], v[168:171], v[212:215], v[24:27]
	v_mfma_f32_16x16x32_bf16 v[12:15], v[152:155], v[220:223], v[12:15]
	v_mfma_f32_16x16x32_bf16 v[8:11], v[168:171], v[220:223], v[8:11]
	v_mfma_f32_16x16x32_bf16 v[60:63], v[160:163], v[196:199], v[60:63]
	v_mfma_f32_16x16x32_bf16 v[56:59], v[172:175], v[196:199], v[56:59]
	v_mfma_f32_16x16x32_bf16 v[44:47], v[160:163], v[208:211], v[44:47]
	v_mfma_f32_16x16x32_bf16 v[40:43], v[172:175], v[208:211], v[40:43]
	v_mfma_f32_16x16x32_bf16 v[28:31], v[160:163], v[216:219], v[28:31]
	v_mfma_f32_16x16x32_bf16 v[24:27], v[172:175], v[216:219], v[24:27]
	v_mfma_f32_16x16x32_bf16 v[12:15], v[160:163], v[224:227], v[12:15]
	v_mfma_f32_16x16x32_bf16 v[8:11], v[172:175], v[224:227], v[8:11]
	s_setprio 0
	s_setprio 1
	v_mfma_f32_16x16x32_bf16 v[52:55], v[176:179], v[192:195], v[52:55]
	v_mfma_f32_16x16x32_bf16 v[48:51], v[184:187], v[192:195], v[48:51]
	v_mfma_f32_16x16x32_bf16 v[36:39], v[176:179], v[204:207], v[36:39]
	v_mfma_f32_16x16x32_bf16 v[32:35], v[184:187], v[204:207], v[32:35]
	v_mfma_f32_16x16x32_bf16 v[20:23], v[176:179], v[212:215], v[20:23]
	v_mfma_f32_16x16x32_bf16 v[16:19], v[184:187], v[212:215], v[16:19]
	v_mfma_f32_16x16x32_bf16 v[4:7], v[176:179], v[220:223], v[4:7]
	v_mfma_f32_16x16x32_bf16 v[0:3], v[184:187], v[220:223], v[0:3]
	v_mfma_f32_16x16x32_bf16 v[52:55], v[180:183], v[196:199], v[52:55]
	v_mfma_f32_16x16x32_bf16 v[48:51], v[188:191], v[196:199], v[48:51]
	v_mfma_f32_16x16x32_bf16 v[36:39], v[180:183], v[208:211], v[36:39]
	v_mfma_f32_16x16x32_bf16 v[32:35], v[188:191], v[208:211], v[32:35]
	v_mfma_f32_16x16x32_bf16 v[20:23], v[180:183], v[216:219], v[20:23]
	v_mfma_f32_16x16x32_bf16 v[16:19], v[188:191], v[216:219], v[16:19]
	v_mfma_f32_16x16x32_bf16 v[4:7], v[180:183], v[224:227], v[4:7]
	v_mfma_f32_16x16x32_bf16 v[0:3], v[188:191], v[224:227], v[0:3]
	s_setprio 0
	s_barrier
	s_add_i32 vcc_hi, vcc_hi, 2
	s_add_u32 s84, s84, 0x100
	s_addc_u32 s85, s85, 0
	s_add_u32 s27, s27, 0x100
	s_addc_u32 vcc_lo, vcc_lo, 0
	s_cmp_gt_u32 vcc_hi, 29

; #define PG8_STAGE(bufoff, gbase, voff) do { _Pragma("unroll") for (int _i = 0; _i < 2; ++_i) \
;         __builtin_amdgcn_global_load_lds((const unsigned*)((const char*)(gbase) + (voff)[_i]), (LAS unsigned*)(lds + (bufoff) + ldsw + _i * 8192), 16, 0, 0); } while (0)
; #define PG8_LDA(dst, b, h) do { _Pragma("unroll") for (int m = 0; m < 4; ++m) _Pragma("unroll") for (int k = 0; k < 2; ++k) dst[m][k] = *(const LAS bf16x8*)(lds + PG8_SA(b, h) + aoff + m * 2048 + k * 1024); } while (0)
; #define PG8_LDB(dst, b, h) do { _Pragma("unroll") for (int n = 0; n < 2; ++n) _Pragma("unroll") for (int k = 0; k < 2; ++k) dst[n][k] = *(const LAS bf16x8*)(lds + PG8_SB(b, h) + boff + n * 2048 + k * 1024); } while (0)
; #define PG8_MMA(ai, bj, At, Bt) do { __builtin_amdgcn_s_setprio(1); _Pragma("unroll") for (int m = 0; m < 4; ++m) _Pragma("unroll") for (int n = 0; n < 2; ++n) _Pragma("unroll") for (int k = 0; k < 2; ++k) \
;         acc[ai][bj][m][n] = __builtin_amdgcn_mfma_f32_16x16x32_bf16(Bt[n][k], At[m][k], acc[ai][bj][m][n], 0, 0, 0); __builtin_amdgcn_s_setprio(0); } while (0)
; #define PG8_BAR __builtin_amdgcn_s_barrier()
; template <class Epi, bool ALIGN_EPI, class Hook = NoHook>
; __device__ __forceinline__ void gemm_phase(LAS unsigned char* lds, const Gemm g, const StaticOrder& S, const Epi& E, const Hook& HK = Hook()) {
;     ...
;         const bool has_next = S.next(ui + 1, nxt);
;         const char* nA = has_next ? (const char*)g.A + (size_t)nxt.pm * tstepA : cA; const char* nB = has_next ? (const char*)g.Bt + (size_t)nxt.pn * tstepB : cB;
;         for (int t = 0; t < nt; t += 2) {
;             if (Hook::AT > 0 && t == Hook::AT) HK(acc, cur, wr, wc, fr, fq);
;             const bool last = (t == nt - 2);
;             const char* a1 = cA + (size_t)(t + 1) * kstep;
;             const char* a2 = last ? nA : cA + (size_t)(t + 2) * kstep; const char* b2 = last ? nB : cB + (size_t)(t + 2) * kstep;
;             const char* a3 = a2 + kstep; const char* b3 = b2 + kstep;
;             PG8_LDB(B0, 0, 0); PG8_LDB(B1, 0, 1); PG8_SCHED; PG8_LDA(At, 0, 0); PG8_STAGE(PG8_SA(1, 1), a1 + hstepA, voffA);
;             PG8_WAIT_V(8); PG8_WAIT_L(0); PG8_BAR; PG8_MMA(0, 0, At, B0); PG8_MMA(0, 1, At, B1); PG8_BAR; PG8_SCHED;
;             PG8_LDA(At, 0, 1); PG8_STAGE(PG8_SB(0, 0), b2, voffB); PG8_STAGE(PG8_SB(0, 1), b2 + hstepB, voffB); PG8_STAGE(PG8_SA(0, 0), a2, voffA);
.LBB0_127:
	s_add_u32 s6, s28, 0x100
	s_addc_u32 s7, s29, 0
	s_mov_b32 s94, -2
	ds_read_b128 v[128:131], v167
	ds_read_b128 v[132:135], v167 offset:1024
	ds_read_b128 v[160:163], v167 offset:2048
	ds_read_b128 v[170:173], v167 offset:3072
	ds_read_b128 v[174:177], v168
	ds_read_b128 v[178:181], v168 offset:1024
	ds_read_b128 v[182:185], v168 offset:2048
	ds_read_b128 v[186:189], v168 offset:3072
	s_add_u32 s28, s24, 0x100
	s_addc_u32 s29, s25, 0
	s_cmpk_eq_i32 s94, 0x54
	s_cselect_b32 s85, s5, s29
	s_cselect_b32 s84, s4, s28
	s_cselect_b32 s77, s19, s7
	s_cselect_b32 s76, s18, s6
	v_lshl_add_u64 v[164:165], s[24:25], 0, v[152:153]
	s_add_i32 m0, s50, 0xc000
	ds_read_b128 v[190:193], v169
	ds_read_b128 v[194:197], v169 offset:1024
	ds_read_b128 v[204:207], v169 offset:2048
	ds_read_b128 v[208:211], v169 offset:3072
	ds_read_b128 v[212:215], v169 offset:4096
	ds_read_b128 v[216:219], v169 offset:5120
	ds_read_b128 v[220:223], v169 offset:6144
	ds_read_b128 v[224:227], v169 offset:7168
	global_load_lds_dwordx4 v[164:165], off
	v_lshl_add_u64 v[164:165], s[24:25], 0, v[154:155]
	s_add_i32 m0, s50, 0xe000
	s_nop 0
	global_load_lds_dwordx4 v[164:165], off
	s_waitcnt vmcnt(8)
	s_waitcnt lgkmcnt(0)
	s_barrier
	s_setprio 1
	s_waitcnt lgkmcnt(0)
	v_mfma_f32_16x16x32_bf16 v[124:127], v[128:131], v[190:193], 0
	v_mfma_f32_16x16x32_bf16 v[120:123], v[160:163], v[190:193], 0
	v_mfma_f32_16x16x32_bf16 v[116:119], v[128:131], v[204:207], 0
	v_mfma_f32_16x16x32_bf16 v[112:115], v[160:163], v[204:207], 0
	v_mfma_f32_16x16x32_bf16 v[108:111], v[128:131], v[212:215], 0
	v_mfma_f32_16x16x32_bf16 v[100:103], v[160:163], v[212:215], 0
	v_mfma_f32_16x16x32_bf16 v[80:83], v[128:131], v[220:223], 0
	v_mfma_f32_16x16x32_bf16 v[72:75], v[160:163], v[220:223], 0
	v_mfma_f32_16x16x32_bf16 v[124:127], v[132:135], v[194:197], v[124:127]
	v_mfma_f32_16x16x32_bf16 v[120:123], v[170:173], v[194:197], v[120:123]
	v_mfma_f32_16x16x32_bf16 v[116:119], v[132:135], v[208:211], v[116:119]
	v_mfma_f32_16x16x32_bf16 v[112:115], v[170:173], v[208:211], v[112:115]
	v_mfma_f32_16x16x32_bf16 v[108:111], v[132:135], v[216:219], v[108:111]
	v_mfma_f32_16x16x32_bf16 v[100:103], v[170:173], v[216:219], v[100:103]
	v_mfma_f32_16x16x32_bf16 v[80:83], v[132:135], v[224:227], v[80:83]
	v_mfma_f32_16x16x32_bf16 v[72:75], v[170:173], v[224:227], v[72:75]
	s_setprio 0
	s_setprio 1
	v_mfma_f32_16x16x32_bf16 v[104:107], v[174:177], v[190:193], 0
	v_mfma_f32_16x16x32_bf16 v[96:99], v[182:185], v[190:193], 0
	v_mfma_f32_16x16x32_bf16 v[92:95], v[174:177], v[204:207], 0
	v_mfma_f32_16x16x32_bf16 v[88:91], v[182:185], v[204:207], 0
	v_mfma_f32_16x16x32_bf16 v[84:87], v[174:177], v[212:215], 0
	v_mfma_f32_16x16x32_bf16 v[76:79], v[182:185], v[212:215], 0
	v_mfma_f32_16x16x32_bf16 v[68:71], v[174:177], v[220:223], 0
	v_mfma_f32_16x16x32_bf16 v[64:67], v[182:185], v[220:223], 0
	v_mfma_f32_16x16x32_bf16 v[104:107], v[178:181], v[194:197], v[104:107]
	v_mfma_f32_16x16x32_bf16 v[96:99], v[186:189], v[194:197], v[96:99]
	v_mfma_f32_16x16x32_bf16 v[92:95], v[178:181], v[208:211], v[92:95]
	v_mfma_f32_16x16x32_bf16 v[88:91], v[186:189], v[208:211], v[88:91]
	v_mfma_f32_16x16x32_bf16 v[84:87], v[178:181], v[216:219], v[84:87]
	v_mfma_f32_16x16x32_bf16 v[76:79], v[186:189], v[216:219], v[76:79]
	v_mfma_f32_16x16x32_bf16 v[68:71], v[178:181], v[224:227], v[68:71]
	v_mfma_f32_16x16x32_bf16 v[64:67], v[186:189], v[224:227], v[64:67]
	s_setprio 0
	s_barrier
	s_add_i32 s24, s88, s27
	v_lshl_add_u64 v[164:165], s[76:77], 0, v[146:147]
	s_mov_b32 m0, s24
	ds_read_b128 v[190:193], v169 offset:16384
	ds_read_b128 v[194:197], v169 offset:17408
	ds_read_b128 v[204:207], v169 offset:18432
	ds_read_b128 v[208:211], v169 offset:19456
	ds_read_b128 v[212:215], v169 offset:20480
	ds_read_b128 v[216:219], v169 offset:21504
	ds_read_b128 v[220:223], v169 offset:22528
	ds_read_b128 v[224:227], v169 offset:23552
	global_load_lds_dwordx4 v[164:165], off
	s_add_i32 m0, s24, 0x2000
	s_add_u32 s24, s76, 0x160000
	v_lshl_add_u64 v[198:199], s[76:77], 0, v[150:151]
	s_addc_u32 s25, s77, 0
	s_add_i32 s34, s89, s27
	global_load_lds_dwordx4 v[198:199], off
	v_lshl_add_u64 v[228:229], s[24:25], 0, v[146:147]
	s_mov_b32 m0, s34
	v_lshl_add_u64 v[230:231], s[84:85], 0, v[148:149]
	global_load_lds_dwordx4 v[228:229], off
	v_lshl_add_u64 v[228:229], s[24:25], 0, v[150:151]
	s_add_i32 m0, s34, 0x2000
	s_nop 0
	global_load_lds_dwordx4 v[228:229], off
	v_lshl_add_u64 v[228:229], s[84:85], 0, v[144:145]
	s_mov_b32 m0, s50
	s_nop 0
	global_load_lds_dwordx4 v[228:229], off
	s_mov_b32 m0, s51
	s_nop 0
	global_load_lds_dwordx4 v[230:231], off
	s_waitcnt vmcnt(8)
	s_waitcnt lgkmcnt(0)
	s_barrier
; #define PG8_STAGE(bufoff, gbase, voff) do { _Pragma("unroll") for (int _i = 0; _i < 2; ++_i) \
;         __builtin_amdgcn_global_load_lds((const unsigned*)((const char*)(gbase) + (voff)[_i]), (LAS unsigned*)(lds + (bufoff) + ldsw + _i * 8192), 16, 0, 0); } while (0)
; #define PG8_LDA(dst, b, h) do { _Pragma("unroll") for (int m = 0; m < 4; ++m) _Pragma("unroll") for (int k = 0; k < 2; ++k) dst[m][k] = *(const LAS bf16x8*)(lds + PG8_SA(b, h) + aoff + m * 2048 + k * 1024); } while (0)
; #define PG8_LDB(dst, b, h) do { _Pragma("unroll") for (int n = 0; n < 2; ++n) _Pragma("unroll") for (int k = 0; k < 2; ++k) dst[n][k] = *(const LAS bf16x8*)(lds + PG8_SB(b, h) + boff + n * 2048 + k * 1024); } while (0)
; #define PG8_MMA(ai, bj, At, Bt) do { __builtin_amdgcn_s_setprio(1); _Pragma("unroll") for (int m = 0; m < 4; ++m) _Pragma("unroll") for (int n = 0; n < 2; ++n) _Pragma("unroll") for (int k = 0; k < 2; ++k) \
;         acc[ai][bj][m][n] = __builtin_amdgcn_mfma_f32_16x16x32_bf16(Bt[n][k], At[m][k], acc[ai][bj][m][n], 0, 0, 0); __builtin_amdgcn_s_setprio(0); } while (0)
; #define PG8_WAIT_V(n) asm volatile("s_waitcnt vmcnt(" #n ")" ::: "memory")
; #define PG8_WAIT_L(n) asm volatile("s_waitcnt lgkmcnt(" #n ")" ::: "memory")
; #define PG8_BAR __builtin_amdgcn_s_barrier()
; #define PG8_SCHED __builtin_amdgcn_sched_barrier(0)
; template <class Epi, bool ALIGN_EPI, class Hook = NoHook>
; __device__ __forceinline__ void gemm_phase(LAS unsigned char* lds, const Gemm g, const StaticOrder& S, const Epi& E, const Hook& HK = Hook()) {
;     ...
;             PG8_WAIT_V(8); PG8_WAIT_L(0); PG8_BAR; PG8_MMA(1, 0, At, B0); PG8_MMA(1, 1, At, B1); PG8_BAR; PG8_SCHED;
;             PG8_LDB(B0, 1, 0); PG8_LDB(B1, 1, 1); PG8_SCHED; PG8_LDA(At, 1, 0); PG8_STAGE(PG8_SA(0, 1), a2 + hstepA, voffA);
;             PG8_WAIT_V(8); PG8_WAIT_L(0); PG8_BAR; PG8_MMA(0, 0, At, B0); PG8_MMA(0, 1, At, B1); PG8_BAR; PG8_SCHED;
	s_setprio 1
	s_waitcnt lgkmcnt(0)
	v_mfma_f32_16x16x32_bf16 v[60:63], v[128:131], v[190:193], 0
	v_mfma_f32_16x16x32_bf16 v[56:59], v[160:163], v[190:193], 0
	v_mfma_f32_16x16x32_bf16 v[52:55], v[128:131], v[204:207], 0
	v_mfma_f32_16x16x32_bf16 v[48:51], v[160:163], v[204:207], 0
	v_mfma_f32_16x16x32_bf16 v[32:35], v[128:131], v[212:215], 0
	v_mfma_f32_16x16x32_bf16 v[24:27], v[160:163], v[212:215], 0
	v_mfma_f32_16x16x32_bf16 v[16:19], v[128:131], v[220:223], 0
	v_mfma_f32_16x16x32_bf16 v[8:11], v[160:163], v[220:223], 0
	v_mfma_f32_16x16x32_bf16 v[60:63], v[132:135], v[194:197], v[60:63]
	v_mfma_f32_16x16x32_bf16 v[56:59], v[170:173], v[194:197], v[56:59]
	v_mfma_f32_16x16x32_bf16 v[52:55], v[132:135], v[208:211], v[52:55]
	v_mfma_f32_16x16x32_bf16 v[48:51], v[170:173], v[208:211], v[48:51]
	v_mfma_f32_16x16x32_bf16 v[32:35], v[132:135], v[216:219], v[32:35]
	v_mfma_f32_16x16x32_bf16 v[24:27], v[170:173], v[216:219], v[24:27]
	v_mfma_f32_16x16x32_bf16 v[16:19], v[132:135], v[224:227], v[16:19]
	v_mfma_f32_16x16x32_bf16 v[8:11], v[170:173], v[224:227], v[8:11]
	s_setprio 0
	s_setprio 1
	v_mfma_f32_16x16x32_bf16 v[44:47], v[174:177], v[190:193], 0
	v_mfma_f32_16x16x32_bf16 v[40:43], v[182:185], v[190:193], 0
	v_mfma_f32_16x16x32_bf16 v[36:39], v[174:177], v[204:207], 0
	v_mfma_f32_16x16x32_bf16 v[28:31], v[182:185], v[204:207], 0
	v_mfma_f32_16x16x32_bf16 v[20:23], v[174:177], v[212:215], 0
	v_mfma_f32_16x16x32_bf16 v[12:15], v[182:185], v[212:215], 0
	v_mfma_f32_16x16x32_bf16 v[4:7], v[174:177], v[220:223], 0
	v_mfma_f32_16x16x32_bf16 v[0:3], v[182:185], v[220:223], 0
	v_mfma_f32_16x16x32_bf16 v[44:47], v[178:181], v[194:197], v[44:47]
	v_mfma_f32_16x16x32_bf16 v[40:43], v[186:189], v[194:197], v[40:43]
	v_mfma_f32_16x16x32_bf16 v[36:39], v[178:181], v[208:211], v[36:39]
	v_mfma_f32_16x16x32_bf16 v[28:31], v[186:189], v[208:211], v[28:31]
	v_mfma_f32_16x16x32_bf16 v[20:23], v[178:181], v[216:219], v[20:23]
	v_mfma_f32_16x16x32_bf16 v[12:15], v[186:189], v[216:219], v[12:15]
	v_mfma_f32_16x16x32_bf16 v[4:7], v[178:181], v[224:227], v[4:7]
	v_mfma_f32_16x16x32_bf16 v[0:3], v[186:189], v[224:227], v[0:3]
	s_setprio 0
	s_barrier
	s_add_i32 s34, 0, 0x18000
	s_add_i32 s35, 0, 0x1c000
	v_add_u32_e32 v170, s34, v141
	v_add_u32_e32 v186, s35, v141
	ds_read_b128 v[128:131], v170
	ds_read_b128 v[132:135], v170 offset:1024
	ds_read_b128 v[160:163], v170 offset:2048
	ds_read_b128 v[170:173], v170 offset:3072
	ds_read_b128 v[174:177], v186
	ds_read_b128 v[178:181], v186 offset:1024
	ds_read_b128 v[182:185], v186 offset:2048
	ds_read_b128 v[186:189], v186 offset:3072
	s_add_u32 s24, s84, 0x160000
	s_addc_u32 s25, s85, 0
	s_mov_b32 m0, s71
	v_lshl_add_u64 v[232:233], s[24:25], 0, v[144:145]
	ds_read_b128 v[190:193], v169 offset:32768
	ds_read_b128 v[194:197], v169 offset:33792
	ds_read_b128 v[204:207], v169 offset:34816
	ds_read_b128 v[208:211], v169 offset:35840
	ds_read_b128 v[212:215], v169 offset:36864
	ds_read_b128 v[216:219], v169 offset:37888
	ds_read_b128 v[220:223], v169 offset:38912
	ds_read_b128 v[224:227], v169 offset:39936
	global_load_lds_dwordx4 v[232:233], off
	v_lshl_add_u64 v[232:233], s[24:25], 0, v[148:149]
	s_mov_b32 m0, s72
	s_nop 0
	global_load_lds_dwordx4 v[232:233], off
	s_waitcnt vmcnt(8)
	s_waitcnt lgkmcnt(0)
	s_barrier
	s_setprio 1
	s_waitcnt lgkmcnt(0)
	v_mfma_f32_16x16x32_bf16 v[124:127], v[128:131], v[190:193], v[124:127]
	v_mfma_f32_16x16x32_bf16 v[120:123], v[160:163], v[190:193], v[120:123]
	v_mfma_f32_16x16x32_bf16 v[116:119], v[128:131], v[204:207], v[116:119]
	v_mfma_f32_16x16x32_bf16 v[112:115], v[160:163], v[204:207], v[112:115]
	v_mfma_f32_16x16x32_bf16 v[108:111], v[128:131], v[212:215], v[108:111]
	v_mfma_f32_16x16x32_bf16 v[100:103], v[160:163], v[212:215], v[100:103]
	v_mfma_f32_16x16x32_bf16 v[80:83], v[128:131], v[220:223], v[80:83]
	v_mfma_f32_16x16x32_bf16 v[72:75], v[160:163], v[220:223], v[72:75]
	v_mfma_f32_16x16x32_bf16 v[124:127], v[132:135], v[194:197], v[124:127]
	v_mfma_f32_16x16x32_bf16 v[120:123], v[170:173], v[194:197], v[120:123]
	v_mfma_f32_16x16x32_bf16 v[116:119], v[132:135], v[208:211], v[116:119]
	v_mfma_f32_16x16x32_bf16 v[112:115], v[170:173], v[208:211], v[112:115]
	v_mfma_f32_16x16x32_bf16 v[108:111], v[132:135], v[216:219], v[108:111]
	v_mfma_f32_16x16x32_bf16 v[100:103], v[170:173], v[216:219], v[100:103]
	v_mfma_f32_16x16x32_bf16 v[80:83], v[132:135], v[224:227], v[80:83]
	v_mfma_f32_16x16x32_bf16 v[72:75], v[170:173], v[224:227], v[72:75]
	s_setprio 0
	s_setprio 1
	v_mfma_f32_16x16x32_bf16 v[104:107], v[174:177], v[190:193], v[104:107]
	v_mfma_f32_16x16x32_bf16 v[96:99], v[182:185], v[190:193], v[96:99]
	v_mfma_f32_16x16x32_bf16 v[92:95], v[174:177], v[204:207], v[92:95]
	v_mfma_f32_16x16x32_bf16 v[88:91], v[182:185], v[204:207], v[88:91]
	v_mfma_f32_16x16x32_bf16 v[84:87], v[174:177], v[212:215], v[84:87]
	v_mfma_f32_16x16x32_bf16 v[76:79], v[182:185], v[212:215], v[76:79]
	v_mfma_f32_16x16x32_bf16 v[68:71], v[174:177], v[220:223], v[68:71]
	v_mfma_f32_16x16x32_bf16 v[64:67], v[182:185], v[220:223], v[64:67]
	v_mfma_f32_16x16x32_bf16 v[104:107], v[178:181], v[194:197], v[104:107]
	v_mfma_f32_16x16x32_bf16 v[96:99], v[186:189], v[194:197], v[96:99]
	v_mfma_f32_16x16x32_bf16 v[92:95], v[178:181], v[208:211], v[92:95]
	v_mfma_f32_16x16x32_bf16 v[88:91], v[186:189], v[208:211], v[88:91]
	v_mfma_f32_16x16x32_bf16 v[84:87], v[178:181], v[216:219], v[84:87]
	v_mfma_f32_16x16x32_bf16 v[76:79], v[186:189], v[216:219], v[76:79]
	v_mfma_f32_16x16x32_bf16 v[68:71], v[178:181], v[224:227], v[68:71]
	v_mfma_f32_16x16x32_bf16 v[64:67], v[186:189], v[224:227], v[64:67]
	s_setprio 0
	s_barrier
; #define PG8_STAGE(bufoff, gbase, voff) do { _Pragma("unroll") for (int _i = 0; _i < 2; ++_i) \
;         __builtin_amdgcn_global_load_lds((const unsigned*)((const char*)(gbase) + (voff)[_i]), (LAS unsigned*)(lds + (bufoff) + ldsw + _i * 8192), 16, 0, 0); } while (0)
; #define PG8_LDA(dst, b, h) do { _Pragma("unroll") for (int m = 0; m < 4; ++m) _Pragma("unroll") for (int k = 0; k < 2; ++k) dst[m][k] = *(const LAS bf16x8*)(lds + PG8_SA(b, h) + aoff + m * 2048 + k * 1024); } while (0)
; #define PG8_MMA(ai, bj, At, Bt) do { __builtin_amdgcn_s_setprio(1); _Pragma("unroll") for (int m = 0; m < 4; ++m) _Pragma("unroll") for (int n = 0; n < 2; ++n) _Pragma("unroll") for (int k = 0; k < 2; ++k) \
;         acc[ai][bj][m][n] = __builtin_amdgcn_mfma_f32_16x16x32_bf16(Bt[n][k], At[m][k], acc[ai][bj][m][n], 0, 0, 0); __builtin_amdgcn_s_setprio(0); } while (0)
; #define PG8_WAIT_V(n) asm volatile("s_waitcnt vmcnt(" #n ")" ::: "memory")
; #define PG8_WAIT_L(n) asm volatile("s_waitcnt lgkmcnt(" #n ")" ::: "memory")
; #define PG8_BAR __builtin_amdgcn_s_barrier()
; #define PG8_SCHED __builtin_amdgcn_sched_barrier(0)
; template <class Epi, bool ALIGN_EPI, class Hook = NoHook>
; __device__ __forceinline__ void gemm_phase(LAS unsigned char* lds, const Gemm g, const StaticOrder& S, const Epi& E, const Hook& HK = Hook()) {
;     ...
;             PG8_LDA(At, 1, 1); PG8_STAGE(PG8_SB(1, 0), b3, voffB); PG8_STAGE(PG8_SB(1, 1), b3 + hstepB, voffB); PG8_STAGE(PG8_SA(1, 0), a3, voffA);
;             PG8_WAIT_V(8); PG8_WAIT_L(0); PG8_BAR; PG8_MMA(1, 0, At, B0); PG8_MMA(1, 1, At, B1); PG8_BAR; PG8_SCHED;
	s_add_i32 s24, s34, s27
	v_lshl_add_u64 v[164:165], v[164:165], 0, s[14:15]
	s_mov_b32 m0, s24
	ds_read_b128 v[190:193], v169 offset:49152
	ds_read_b128 v[194:197], v169 offset:50176
	ds_read_b128 v[204:207], v169 offset:51200
	ds_read_b128 v[208:211], v169 offset:52224
	ds_read_b128 v[212:215], v169 offset:53248
	ds_read_b128 v[216:219], v169 offset:54272
	ds_read_b128 v[220:223], v169 offset:55296
	ds_read_b128 v[224:227], v169 offset:56320
	global_load_lds_dwordx4 v[164:165], off
	s_add_i32 m0, s24, 0x2000
	s_add_u32 s24, s76, 0x160080
	v_lshl_add_u64 v[164:165], v[198:199], 0, s[14:15]
	s_addc_u32 s25, s77, 0
	s_add_i32 s34, s35, s27
	global_load_lds_dwordx4 v[164:165], off
	v_lshl_add_u64 v[164:165], s[24:25], 0, v[146:147]
	s_mov_b32 m0, s34
	s_nop 0
	global_load_lds_dwordx4 v[164:165], off
	v_lshl_add_u64 v[164:165], s[24:25], 0, v[150:151]
	s_add_i32 m0, s34, 0x2000
	s_nop 0
	global_load_lds_dwordx4 v[164:165], off
	v_lshl_add_u64 v[164:165], v[228:229], 0, s[14:15]
	s_mov_b32 m0, s82
	s_nop 0
	global_load_lds_dwordx4 v[164:165], off
	v_lshl_add_u64 v[164:165], v[230:231], 0, s[14:15]
	s_mov_b32 m0, s83
	s_nop 0
	global_load_lds_dwordx4 v[164:165], off
	s_waitcnt vmcnt(8)
	s_waitcnt lgkmcnt(0)
	s_barrier
	s_setprio 1
	s_waitcnt lgkmcnt(0)
	v_mfma_f32_16x16x32_bf16 v[60:63], v[128:131], v[190:193], v[60:63]
	v_mfma_f32_16x16x32_bf16 v[56:59], v[160:163], v[190:193], v[56:59]
	v_mfma_f32_16x16x32_bf16 v[52:55], v[128:131], v[204:207], v[52:55]
	v_mfma_f32_16x16x32_bf16 v[48:51], v[160:163], v[204:207], v[48:51]
	v_mfma_f32_16x16x32_bf16 v[32:35], v[128:131], v[212:215], v[32:35]
	v_mfma_f32_16x16x32_bf16 v[24:27], v[160:163], v[212:215], v[24:27]
	v_mfma_f32_16x16x32_bf16 v[16:19], v[128:131], v[220:223], v[16:19]
	v_mfma_f32_16x16x32_bf16 v[8:11], v[160:163], v[220:223], v[8:11]
	v_mfma_f32_16x16x32_bf16 v[60:63], v[132:135], v[194:197], v[60:63]
	v_mfma_f32_16x16x32_bf16 v[56:59], v[170:173], v[194:197], v[56:59]
	v_mfma_f32_16x16x32_bf16 v[52:55], v[132:135], v[208:211], v[52:55]
	v_mfma_f32_16x16x32_bf16 v[48:51], v[170:173], v[208:211], v[48:51]
	v_mfma_f32_16x16x32_bf16 v[32:35], v[132:135], v[216:219], v[32:35]
	v_mfma_f32_16x16x32_bf16 v[24:27], v[170:173], v[216:219], v[24:27]
	v_mfma_f32_16x16x32_bf16 v[16:19], v[132:135], v[224:227], v[16:19]
	v_mfma_f32_16x16x32_bf16 v[8:11], v[170:173], v[224:227], v[8:11]
	s_setprio 0
	s_setprio 1
	v_mfma_f32_16x16x32_bf16 v[44:47], v[174:177], v[190:193], v[44:47]
	v_mfma_f32_16x16x32_bf16 v[40:43], v[182:185], v[190:193], v[40:43]
	v_mfma_f32_16x16x32_bf16 v[36:39], v[174:177], v[204:207], v[36:39]
	v_mfma_f32_16x16x32_bf16 v[28:31], v[182:185], v[204:207], v[28:31]
	v_mfma_f32_16x16x32_bf16 v[20:23], v[174:177], v[212:215], v[20:23]
	v_mfma_f32_16x16x32_bf16 v[12:15], v[182:185], v[212:215], v[12:15]
	v_mfma_f32_16x16x32_bf16 v[4:7], v[174:177], v[220:223], v[4:7]
	v_mfma_f32_16x16x32_bf16 v[0:3], v[182:185], v[220:223], v[0:3]
	v_mfma_f32_16x16x32_bf16 v[44:47], v[178:181], v[194:197], v[44:47]
	v_mfma_f32_16x16x32_bf16 v[40:43], v[186:189], v[194:197], v[40:43]
	v_mfma_f32_16x16x32_bf16 v[36:39], v[178:181], v[208:211], v[36:39]
	v_mfma_f32_16x16x32_bf16 v[28:31], v[186:189], v[208:211], v[28:31]
	v_mfma_f32_16x16x32_bf16 v[20:23], v[178:181], v[216:219], v[20:23]
	v_mfma_f32_16x16x32_bf16 v[12:15], v[186:189], v[216:219], v[12:15]
	v_mfma_f32_16x16x32_bf16 v[4:7], v[178:181], v[224:227], v[4:7]
	v_mfma_f32_16x16x32_bf16 v[0:3], v[186:189], v[224:227], v[0:3]
	s_setprio 0
	s_barrier
	s_add_i32 s94, s94, 2
	s_add_u32 s6, s6, 0x100
	s_addc_u32 s7, s7, 0
	s_cmpk_gt_u32 s94, 0x55
	s_mov_b64 s[24:25], s[28:29]

; #define PG8_STAGE(bufoff, gbase, voff) do { _Pragma("unroll") for (int _i = 0; _i < 2; ++_i) \
;         __builtin_amdgcn_global_load_lds((const unsigned*)((const char*)(gbase) + (voff)[_i]), (LAS unsigned*)(lds + (bufoff) + ldsw + _i * 8192), 16, 0, 0); } while (0)
; #define PG8_LDA(dst, b, h) do { _Pragma("unroll") for (int m = 0; m < 4; ++m) _Pragma("unroll") for (int k = 0; k < 2; ++k) dst[m][k] = *(const LAS bf16x8*)(lds + PG8_SA(b, h) + aoff + m * 2048 + k * 1024); } while (0)
; #define PG8_LDB(dst, b, h) do { _Pragma("unroll") for (int n = 0; n < 2; ++n) _Pragma("unroll") for (int k = 0; k < 2; ++k) dst[n][k] = *(const LAS bf16x8*)(lds + PG8_SB(b, h) + boff + n * 2048 + k * 1024); } while (0)
; #define PG8_MMA(ai, bj, At, Bt) do { __builtin_amdgcn_s_setprio(1); _Pragma("unroll") for (int m = 0; m < 4; ++m) _Pragma("unroll") for (int n = 0; n < 2; ++n) _Pragma("unroll") for (int k = 0; k < 2; ++k) \
;         acc[ai][bj][m][n] = __builtin_amdgcn_mfma_f32_16x16x32_bf16(Bt[n][k], At[m][k], acc[ai][bj][m][n], 0, 0, 0); __builtin_amdgcn_s_setprio(0); } while (0)
; #define PG8_BAR __builtin_amdgcn_s_barrier()
; template <class Epi, bool ALIGN_EPI, class Hook = NoHook>
; __device__ __forceinline__ void gemm_phase(LAS unsigned char* lds, const Gemm g, const StaticOrder& S, const Epi& E, const Hook& HK = Hook()) {
;     ...
;         const bool has_next = S.next(ui + 1, nxt);
;         const char* nA = has_next ? (const char*)g.A + (size_t)nxt.pm * tstepA : cA; const char* nB = has_next ? (const char*)g.Bt + (size_t)nxt.pn * tstepB : cB;
;         for (int t = 0; t < nt; t += 2) {
;             if (Hook::AT > 0 && t == Hook::AT) HK(acc, cur, wr, wc, fr, fq);
;             const bool last = (t == nt - 2);
;             const char* a1 = cA + (size_t)(t + 1) * kstep;
;             const char* a2 = last ? nA : cA + (size_t)(t + 2) * kstep; const char* b2 = last ? nB : cB + (size_t)(t + 2) * kstep;
;             const char* a3 = a2 + kstep; const char* b3 = b2 + kstep;
;             PG8_LDB(B0, 0, 0); PG8_LDB(B1, 0, 1); PG8_SCHED; PG8_LDA(At, 0, 0); PG8_STAGE(PG8_SA(1, 1), a1 + hstepA, voffA);
;             PG8_WAIT_V(8); PG8_WAIT_L(0); PG8_BAR; PG8_MMA(0, 0, At, B0); PG8_MMA(0, 1, At, B1); PG8_BAR; PG8_SCHED;
;             PG8_LDA(At, 0, 1); PG8_STAGE(PG8_SB(0, 0), b2, voffB); PG8_STAGE(PG8_SB(0, 1), b2 + hstepB, voffB); PG8_STAGE(PG8_SA(0, 0), a2, voffA);
.LBB0_269:
	s_ashr_i32 s19, s18, 31
	s_lshl_b64 s[22:23], s[18:19], 20
	s_add_u32 s22, s48, s22
	s_addc_u32 s23, s49, s23
	s_and_b64 s[24:25], s[0:1], exec
	s_cselect_b32 s5, s23, s87
	s_cselect_b32 s19, s22, s86
	s_ashr_i32 s21, s20, 31
	s_lshl_b64 s[24:25], s[20:21], 20
	s_add_u32 s24, s80, s24
	s_addc_u32 s25, s81, s25
	s_and_b64 s[26:27], s[0:1], exec
	s_cselect_b32 s21, s25, s89
	s_cselect_b32 s26, s24, s88
	s_add_u32 s86, s86, 0x80080
	s_addc_u32 s87, s87, 0
	s_add_u32 s27, s88, 0x100
	s_addc_u32 s50, s89, 0
	s_mov_b32 s51, -2
	ds_read_b128 v[156:159], v141
	ds_read_b128 v[160:163], v141 offset:1024
	ds_read_b128 v[168:171], v141 offset:2048
	ds_read_b128 v[172:175], v141 offset:3072
	ds_read_b128 v[176:179], v143
	ds_read_b128 v[180:183], v143 offset:1024
	ds_read_b128 v[184:187], v143 offset:2048
	ds_read_b128 v[188:191], v143 offset:3072
	s_add_u32 s34, s86, 0xfff80080
	s_addc_u32 s35, s87, -1
	s_cmp_eq_u32 s51, 28
	s_cselect_b32 s91, s5, s35
	s_cselect_b32 s90, s19, s34
	s_cselect_b32 s89, s21, s50
	s_cselect_b32 s88, s26, s27
	v_lshl_add_u64 v[164:165], s[86:87], 0, v[148:149]
	s_add_i32 m0, s28, 0xc000
	ds_read_b128 v[192:195], v167
	ds_read_b128 v[196:199], v167 offset:1024
	ds_read_b128 v[204:207], v167 offset:2048
	ds_read_b128 v[208:211], v167 offset:3072
	ds_read_b128 v[212:215], v167 offset:4096
	ds_read_b128 v[216:219], v167 offset:5120
	ds_read_b128 v[220:223], v167 offset:6144
	ds_read_b128 v[224:227], v167 offset:7168
	global_load_lds_dwordx4 v[164:165], off
	v_lshl_add_u64 v[164:165], s[86:87], 0, v[150:151]
	s_add_i32 m0, s28, 0xe000
	s_nop 0
	global_load_lds_dwordx4 v[164:165], off
	s_waitcnt vmcnt(8)
	s_waitcnt lgkmcnt(0)
	s_barrier
	s_setprio 1
	s_waitcnt lgkmcnt(0)
	v_mfma_f32_16x16x32_bf16 v[124:127], v[156:159], v[192:195], 0
	v_mfma_f32_16x16x32_bf16 v[120:123], v[168:171], v[192:195], 0
	v_mfma_f32_16x16x32_bf16 v[108:111], v[156:159], v[204:207], 0
	v_mfma_f32_16x16x32_bf16 v[104:107], v[168:171], v[204:207], 0
	v_mfma_f32_16x16x32_bf16 v[92:95], v[156:159], v[212:215], 0
	v_mfma_f32_16x16x32_bf16 v[88:91], v[168:171], v[212:215], 0
	v_mfma_f32_16x16x32_bf16 v[76:79], v[156:159], v[220:223], 0
	v_mfma_f32_16x16x32_bf16 v[72:75], v[168:171], v[220:223], 0
	v_mfma_f32_16x16x32_bf16 v[124:127], v[160:163], v[196:199], v[124:127]
	v_mfma_f32_16x16x32_bf16 v[120:123], v[172:175], v[196:199], v[120:123]
	v_mfma_f32_16x16x32_bf16 v[108:111], v[160:163], v[208:211], v[108:111]
	v_mfma_f32_16x16x32_bf16 v[104:107], v[172:175], v[208:211], v[104:107]
	v_mfma_f32_16x16x32_bf16 v[92:95], v[160:163], v[216:219], v[92:95]
	v_mfma_f32_16x16x32_bf16 v[88:91], v[172:175], v[216:219], v[88:91]
	v_mfma_f32_16x16x32_bf16 v[76:79], v[160:163], v[224:227], v[76:79]
	v_mfma_f32_16x16x32_bf16 v[72:75], v[172:175], v[224:227], v[72:75]
	s_setprio 0
	s_setprio 1
	v_mfma_f32_16x16x32_bf16 v[116:119], v[176:179], v[192:195], 0
	v_mfma_f32_16x16x32_bf16 v[112:115], v[184:187], v[192:195], 0
	v_mfma_f32_16x16x32_bf16 v[100:103], v[176:179], v[204:207], 0
	v_mfma_f32_16x16x32_bf16 v[96:99], v[184:187], v[204:207], 0
	v_mfma_f32_16x16x32_bf16 v[84:87], v[176:179], v[212:215], 0
	v_mfma_f32_16x16x32_bf16 v[80:83], v[184:187], v[212:215], 0
	v_mfma_f32_16x16x32_bf16 v[68:71], v[176:179], v[220:223], 0
	v_mfma_f32_16x16x32_bf16 v[64:67], v[184:187], v[220:223], 0
	v_mfma_f32_16x16x32_bf16 v[116:119], v[180:183], v[196:199], v[116:119]
	v_mfma_f32_16x16x32_bf16 v[112:115], v[188:191], v[196:199], v[112:115]
	v_mfma_f32_16x16x32_bf16 v[100:103], v[180:183], v[208:211], v[100:103]
	v_mfma_f32_16x16x32_bf16 v[96:99], v[188:191], v[208:211], v[96:99]
	v_mfma_f32_16x16x32_bf16 v[84:87], v[180:183], v[216:219], v[84:87]
	v_mfma_f32_16x16x32_bf16 v[80:83], v[188:191], v[216:219], v[80:83]
	v_mfma_f32_16x16x32_bf16 v[68:71], v[180:183], v[224:227], v[68:71]
	v_mfma_f32_16x16x32_bf16 v[64:67], v[188:191], v[224:227], v[64:67]
	s_setprio 0
	s_barrier
	s_add_i32 s34, s97, s17
	v_lshl_add_u64 v[164:165], s[88:89], 0, v[134:135]
	s_mov_b32 m0, s34
	ds_read_b128 v[192:195], v167 offset:16384
	ds_read_b128 v[196:199], v167 offset:17408
	ds_read_b128 v[204:207], v167 offset:18432
	ds_read_b128 v[208:211], v167 offset:19456
	ds_read_b128 v[212:215], v167 offset:20480
	ds_read_b128 v[216:219], v167 offset:21504
	ds_read_b128 v[220:223], v167 offset:22528
	ds_read_b128 v[224:227], v167 offset:23552
	global_load_lds_dwordx4 v[164:165], off
	s_add_i32 m0, s34, 0x2000
	s_add_u32 s34, s88, 0x80000
	v_lshl_add_u64 v[228:229], s[88:89], 0, v[146:147]
	s_addc_u32 s35, s89, 0
	s_add_i32 s52, s8, s17
	global_load_lds_dwordx4 v[228:229], off
	v_lshl_add_u64 v[230:231], s[34:35], 0, v[134:135]
	s_mov_b32 m0, s52
	v_lshl_add_u64 v[232:233], s[90:91], 0, v[144:145]
	global_load_lds_dwordx4 v[230:231], off
	v_lshl_add_u64 v[230:231], s[34:35], 0, v[146:147]
	s_add_i32 m0, s52, 0x2000
	s_nop 0
	global_load_lds_dwordx4 v[230:231], off
	v_lshl_add_u64 v[230:231], s[90:91], 0, v[130:131]
	s_mov_b32 m0, s28
	s_nop 0
	global_load_lds_dwordx4 v[230:231], off
	s_mov_b32 m0, s29
	s_nop 0
	global_load_lds_dwordx4 v[232:233], off
	s_waitcnt vmcnt(8)
	s_waitcnt lgkmcnt(0)
	s_barrier
; #define PG8_STAGE(bufoff, gbase, voff) do { _Pragma("unroll") for (int _i = 0; _i < 2; ++_i) \
;         __builtin_amdgcn_global_load_lds((const unsigned*)((const char*)(gbase) + (voff)[_i]), (LAS unsigned*)(lds + (bufoff) + ldsw + _i * 8192), 16, 0, 0); } while (0)
; #define PG8_LDA(dst, b, h) do { _Pragma("unroll") for (int m = 0; m < 4; ++m) _Pragma("unroll") for (int k = 0; k < 2; ++k) dst[m][k] = *(const LAS bf16x8*)(lds + PG8_SA(b, h) + aoff + m * 2048 + k * 1024); } while (0)
; #define PG8_LDB(dst, b, h) do { _Pragma("unroll") for (int n = 0; n < 2; ++n) _Pragma("unroll") for (int k = 0; k < 2; ++k) dst[n][k] = *(const LAS bf16x8*)(lds + PG8_SB(b, h) + boff + n * 2048 + k * 1024); } while (0)
; #define PG8_MMA(ai, bj, At, Bt) do { __builtin_amdgcn_s_setprio(1); _Pragma("unroll") for (int m = 0; m < 4; ++m) _Pragma("unroll") for (int n = 0; n < 2; ++n) _Pragma("unroll") for (int k = 0; k < 2; ++k) \
;         acc[ai][bj][m][n] = __builtin_amdgcn_mfma_f32_16x16x32_bf16(Bt[n][k], At[m][k], acc[ai][bj][m][n], 0, 0, 0); __builtin_amdgcn_s_setprio(0); } while (0)
; #define PG8_WAIT_V(n) asm volatile("s_waitcnt vmcnt(" #n ")" ::: "memory")
; #define PG8_WAIT_L(n) asm volatile("s_waitcnt lgkmcnt(" #n ")" ::: "memory")
; #define PG8_BAR __builtin_amdgcn_s_barrier()
; #define PG8_SCHED __builtin_amdgcn_sched_barrier(0)
; template <class Epi, bool ALIGN_EPI, class Hook = NoHook>
; __device__ __forceinline__ void gemm_phase(LAS unsigned char* lds, const Gemm g, const StaticOrder& S, const Epi& E, const Hook& HK = Hook()) {
;     ...
;             PG8_WAIT_V(8); PG8_WAIT_L(0); PG8_BAR; PG8_MMA(1, 0, At, B0); PG8_MMA(1, 1, At, B1); PG8_BAR; PG8_SCHED;
;             PG8_LDB(B0, 1, 0); PG8_LDB(B1, 1, 1); PG8_SCHED; PG8_LDA(At, 1, 0); PG8_STAGE(PG8_SA(0, 1), a2 + hstepA, voffA);
;             PG8_WAIT_V(8); PG8_WAIT_L(0); PG8_BAR; PG8_MMA(0, 0, At, B0); PG8_MMA(0, 1, At, B1); PG8_BAR; PG8_SCHED;
	s_setprio 1
	s_waitcnt lgkmcnt(0)
	v_mfma_f32_16x16x32_bf16 v[60:63], v[156:159], v[192:195], 0
	v_mfma_f32_16x16x32_bf16 v[56:59], v[168:171], v[192:195], 0
	v_mfma_f32_16x16x32_bf16 v[44:47], v[156:159], v[204:207], 0
	v_mfma_f32_16x16x32_bf16 v[40:43], v[168:171], v[204:207], 0
	v_mfma_f32_16x16x32_bf16 v[28:31], v[156:159], v[212:215], 0
	v_mfma_f32_16x16x32_bf16 v[24:27], v[168:171], v[212:215], 0
	v_mfma_f32_16x16x32_bf16 v[12:15], v[156:159], v[220:223], 0
	v_mfma_f32_16x16x32_bf16 v[8:11], v[168:171], v[220:223], 0
	v_mfma_f32_16x16x32_bf16 v[60:63], v[160:163], v[196:199], v[60:63]
	v_mfma_f32_16x16x32_bf16 v[56:59], v[172:175], v[196:199], v[56:59]
	v_mfma_f32_16x16x32_bf16 v[44:47], v[160:163], v[208:211], v[44:47]
	v_mfma_f32_16x16x32_bf16 v[40:43], v[172:175], v[208:211], v[40:43]
	v_mfma_f32_16x16x32_bf16 v[28:31], v[160:163], v[216:219], v[28:31]
	v_mfma_f32_16x16x32_bf16 v[24:27], v[172:175], v[216:219], v[24:27]
	v_mfma_f32_16x16x32_bf16 v[12:15], v[160:163], v[224:227], v[12:15]
	v_mfma_f32_16x16x32_bf16 v[8:11], v[172:175], v[224:227], v[8:11]
	s_setprio 0
	s_setprio 1
	v_mfma_f32_16x16x32_bf16 v[52:55], v[176:179], v[192:195], 0
	v_mfma_f32_16x16x32_bf16 v[48:51], v[184:187], v[192:195], 0
	v_mfma_f32_16x16x32_bf16 v[36:39], v[176:179], v[204:207], 0
	v_mfma_f32_16x16x32_bf16 v[32:35], v[184:187], v[204:207], 0
	v_mfma_f32_16x16x32_bf16 v[20:23], v[176:179], v[212:215], 0
	v_mfma_f32_16x16x32_bf16 v[16:19], v[184:187], v[212:215], 0
	v_mfma_f32_16x16x32_bf16 v[4:7], v[176:179], v[220:223], 0
	v_mfma_f32_16x16x32_bf16 v[0:3], v[184:187], v[220:223], 0
	v_mfma_f32_16x16x32_bf16 v[52:55], v[180:183], v[196:199], v[52:55]
	v_mfma_f32_16x16x32_bf16 v[48:51], v[188:191], v[196:199], v[48:51]
	v_mfma_f32_16x16x32_bf16 v[36:39], v[180:183], v[208:211], v[36:39]
	v_mfma_f32_16x16x32_bf16 v[32:35], v[188:191], v[208:211], v[32:35]
	v_mfma_f32_16x16x32_bf16 v[20:23], v[180:183], v[216:219], v[20:23]
	v_mfma_f32_16x16x32_bf16 v[16:19], v[188:191], v[216:219], v[16:19]
	v_mfma_f32_16x16x32_bf16 v[4:7], v[180:183], v[224:227], v[4:7]
	v_mfma_f32_16x16x32_bf16 v[0:3], v[188:191], v[224:227], v[0:3]
	s_setprio 0
	s_barrier
	s_add_i32 s52, 0, 0x18000
	s_add_i32 s53, 0, 0x1c000
	v_add_u32_e32 v172, s52, v133
	v_add_u32_e32 v188, s53, v133
	ds_read_b128 v[156:159], v172
	ds_read_b128 v[160:163], v172 offset:1024
	ds_read_b128 v[168:171], v172 offset:2048
	ds_read_b128 v[172:175], v172 offset:3072
	ds_read_b128 v[176:179], v188
	ds_read_b128 v[180:183], v188 offset:1024
	ds_read_b128 v[184:187], v188 offset:2048
	ds_read_b128 v[188:191], v188 offset:3072
	s_add_u32 s34, s90, 0x80000
	s_addc_u32 s35, s91, 0
	s_mov_b32 m0, s71
	v_lshl_add_u64 v[234:235], s[34:35], 0, v[130:131]
	ds_read_b128 v[192:195], v167 offset:32768
	ds_read_b128 v[196:199], v167 offset:33792
	ds_read_b128 v[204:207], v167 offset:34816
	ds_read_b128 v[208:211], v167 offset:35840
	ds_read_b128 v[212:215], v167 offset:36864
	ds_read_b128 v[216:219], v167 offset:37888
	ds_read_b128 v[220:223], v167 offset:38912
	ds_read_b128 v[224:227], v167 offset:39936
	global_load_lds_dwordx4 v[234:235], off
	v_lshl_add_u64 v[234:235], s[34:35], 0, v[144:145]
	s_mov_b32 m0, s82
	s_nop 0
	global_load_lds_dwordx4 v[234:235], off
	s_waitcnt vmcnt(8)
	s_waitcnt lgkmcnt(0)
	s_barrier
	s_setprio 1
	s_waitcnt lgkmcnt(0)
	v_mfma_f32_16x16x32_bf16 v[124:127], v[156:159], v[192:195], v[124:127]
	v_mfma_f32_16x16x32_bf16 v[120:123], v[168:171], v[192:195], v[120:123]
	v_mfma_f32_16x16x32_bf16 v[108:111], v[156:159], v[204:207], v[108:111]
	v_mfma_f32_16x16x32_bf16 v[104:107], v[168:171], v[204:207], v[104:107]
	v_mfma_f32_16x16x32_bf16 v[92:95], v[156:159], v[212:215], v[92:95]
	v_mfma_f32_16x16x32_bf16 v[88:91], v[168:171], v[212:215], v[88:91]
	v_mfma_f32_16x16x32_bf16 v[76:79], v[156:159], v[220:223], v[76:79]
	v_mfma_f32_16x16x32_bf16 v[72:75], v[168:171], v[220:223], v[72:75]
	v_mfma_f32_16x16x32_bf16 v[124:127], v[160:163], v[196:199], v[124:127]
	v_mfma_f32_16x16x32_bf16 v[120:123], v[172:175], v[196:199], v[120:123]
	v_mfma_f32_16x16x32_bf16 v[108:111], v[160:163], v[208:211], v[108:111]
	v_mfma_f32_16x16x32_bf16 v[104:107], v[172:175], v[208:211], v[104:107]
	v_mfma_f32_16x16x32_bf16 v[92:95], v[160:163], v[216:219], v[92:95]
	v_mfma_f32_16x16x32_bf16 v[88:91], v[172:175], v[216:219], v[88:91]
	v_mfma_f32_16x16x32_bf16 v[76:79], v[160:163], v[224:227], v[76:79]
	v_mfma_f32_16x16x32_bf16 v[72:75], v[172:175], v[224:227], v[72:75]
	s_setprio 0
	s_setprio 1
	v_mfma_f32_16x16x32_bf16 v[116:119], v[176:179], v[192:195], v[116:119]
	v_mfma_f32_16x16x32_bf16 v[112:115], v[184:187], v[192:195], v[112:115]
	v_mfma_f32_16x16x32_bf16 v[100:103], v[176:179], v[204:207], v[100:103]
	v_mfma_f32_16x16x32_bf16 v[96:99], v[184:187], v[204:207], v[96:99]
	v_mfma_f32_16x16x32_bf16 v[84:87], v[176:179], v[212:215], v[84:87]
	v_mfma_f32_16x16x32_bf16 v[80:83], v[184:187], v[212:215], v[80:83]
	v_mfma_f32_16x16x32_bf16 v[68:71], v[176:179], v[220:223], v[68:71]
	v_mfma_f32_16x16x32_bf16 v[64:67], v[184:187], v[220:223], v[64:67]
	v_mfma_f32_16x16x32_bf16 v[116:119], v[180:183], v[196:199], v[116:119]
	v_mfma_f32_16x16x32_bf16 v[112:115], v[188:191], v[196:199], v[112:115]
	v_mfma_f32_16x16x32_bf16 v[100:103], v[180:183], v[208:211], v[100:103]
	v_mfma_f32_16x16x32_bf16 v[96:99], v[188:191], v[208:211], v[96:99]
	v_mfma_f32_16x16x32_bf16 v[84:87], v[180:183], v[216:219], v[84:87]
	v_mfma_f32_16x16x32_bf16 v[80:83], v[188:191], v[216:219], v[80:83]
	v_mfma_f32_16x16x32_bf16 v[68:71], v[180:183], v[224:227], v[68:71]
	v_mfma_f32_16x16x32_bf16 v[64:67], v[188:191], v[224:227], v[64:67]
	s_setprio 0
	s_barrier
; #define PG8_STAGE(bufoff, gbase, voff) do { _Pragma("unroll") for (int _i = 0; _i < 2; ++_i) \
;         __builtin_amdgcn_global_load_lds((const unsigned*)((const char*)(gbase) + (voff)[_i]), (LAS unsigned*)(lds + (bufoff) + ldsw + _i * 8192), 16, 0, 0); } while (0)
; #define PG8_LDA(dst, b, h) do { _Pragma("unroll") for (int m = 0; m < 4; ++m) _Pragma("unroll") for (int k = 0; k < 2; ++k) dst[m][k] = *(const LAS bf16x8*)(lds + PG8_SA(b, h) + aoff + m * 2048 + k * 1024); } while (0)
; #define PG8_MMA(ai, bj, At, Bt) do { __builtin_amdgcn_s_setprio(1); _Pragma("unroll") for (int m = 0; m < 4; ++m) _Pragma("unroll") for (int n = 0; n < 2; ++n) _Pragma("unroll") for (int k = 0; k < 2; ++k) \
;         acc[ai][bj][m][n] = __builtin_amdgcn_mfma_f32_16x16x32_bf16(Bt[n][k], At[m][k], acc[ai][bj][m][n], 0, 0, 0); __builtin_amdgcn_s_setprio(0); } while (0)
; #define PG8_WAIT_V(n) asm volatile("s_waitcnt vmcnt(" #n ")" ::: "memory")
; #define PG8_WAIT_L(n) asm volatile("s_waitcnt lgkmcnt(" #n ")" ::: "memory")
; #define PG8_BAR __builtin_amdgcn_s_barrier()
; #define PG8_SCHED __builtin_amdgcn_sched_barrier(0)
; template <class Epi, bool ALIGN_EPI, class Hook = NoHook>
; __device__ __forceinline__ void gemm_phase(LAS unsigned char* lds, const Gemm g, const StaticOrder& S, const Epi& E, const Hook& HK = Hook()) {
;     ...
;             PG8_LDA(At, 1, 1); PG8_STAGE(PG8_SB(1, 0), b3, voffB); PG8_STAGE(PG8_SB(1, 1), b3 + hstepB, voffB); PG8_STAGE(PG8_SA(1, 0), a3, voffA);
;             PG8_WAIT_V(8); PG8_WAIT_L(0); PG8_BAR; PG8_MMA(1, 0, At, B0); PG8_MMA(1, 1, At, B1); PG8_BAR; PG8_SCHED;
	s_add_i32 s34, s52, s17
	v_lshl_add_u64 v[164:165], v[164:165], 0, s[12:13]
	s_mov_b32 m0, s34
	ds_read_b128 v[192:195], v167 offset:49152
	ds_read_b128 v[196:199], v167 offset:50176
	ds_read_b128 v[204:207], v167 offset:51200
	ds_read_b128 v[208:211], v167 offset:52224
	ds_read_b128 v[212:215], v167 offset:53248
	ds_read_b128 v[216:219], v167 offset:54272
	ds_read_b128 v[220:223], v167 offset:55296
	ds_read_b128 v[224:227], v167 offset:56320
	global_load_lds_dwordx4 v[164:165], off
	s_add_i32 m0, s34, 0x2000
	s_add_u32 s34, s88, 0x80080
	v_lshl_add_u64 v[164:165], v[228:229], 0, s[12:13]
	s_addc_u32 s35, s89, 0
	s_add_i32 s52, s53, s17
	global_load_lds_dwordx4 v[164:165], off
	v_lshl_add_u64 v[164:165], s[34:35], 0, v[134:135]
	s_mov_b32 m0, s52
	s_nop 0
	global_load_lds_dwordx4 v[164:165], off
	v_lshl_add_u64 v[164:165], s[34:35], 0, v[146:147]
	s_add_i32 m0, s52, 0x2000
	s_nop 0
	global_load_lds_dwordx4 v[164:165], off
	v_lshl_add_u64 v[164:165], v[230:231], 0, s[12:13]
	s_mov_b32 m0, s92
	s_nop 0
	global_load_lds_dwordx4 v[164:165], off
	v_lshl_add_u64 v[164:165], v[232:233], 0, s[12:13]
	s_mov_b32 m0, s93
	s_nop 0
	global_load_lds_dwordx4 v[164:165], off
	s_waitcnt vmcnt(8)
	s_waitcnt lgkmcnt(0)
	s_barrier
	s_setprio 1
	s_waitcnt lgkmcnt(0)
	v_mfma_f32_16x16x32_bf16 v[60:63], v[156:159], v[192:195], v[60:63]
	v_mfma_f32_16x16x32_bf16 v[56:59], v[168:171], v[192:195], v[56:59]
	v_mfma_f32_16x16x32_bf16 v[44:47], v[156:159], v[204:207], v[44:47]
	v_mfma_f32_16x16x32_bf16 v[40:43], v[168:171], v[204:207], v[40:43]
	v_mfma_f32_16x16x32_bf16 v[28:31], v[156:159], v[212:215], v[28:31]
	v_mfma_f32_16x16x32_bf16 v[24:27], v[168:171], v[212:215], v[24:27]
	v_mfma_f32_16x16x32_bf16 v[12:15], v[156:159], v[220:223], v[12:15]
	v_mfma_f32_16x16x32_bf16 v[8:11], v[168:171], v[220:223], v[8:11]
	v_mfma_f32_16x16x32_bf16 v[60:63], v[160:163], v[196:199], v[60:63]
	v_mfma_f32_16x16x32_bf16 v[56:59], v[172:175], v[196:199], v[56:59]
	v_mfma_f32_16x16x32_bf16 v[44:47], v[160:163], v[208:211], v[44:47]
	v_mfma_f32_16x16x32_bf16 v[40:43], v[172:175], v[208:211], v[40:43]
	v_mfma_f32_16x16x32_bf16 v[28:31], v[160:163], v[216:219], v[28:31]
	v_mfma_f32_16x16x32_bf16 v[24:27], v[172:175], v[216:219], v[24:27]
	v_mfma_f32_16x16x32_bf16 v[12:15], v[160:163], v[224:227], v[12:15]
	v_mfma_f32_16x16x32_bf16 v[8:11], v[172:175], v[224:227], v[8:11]
	s_setprio 0
	s_setprio 1
	v_mfma_f32_16x16x32_bf16 v[52:55], v[176:179], v[192:195], v[52:55]
	v_mfma_f32_16x16x32_bf16 v[48:51], v[184:187], v[192:195], v[48:51]
	v_mfma_f32_16x16x32_bf16 v[36:39], v[176:179], v[204:207], v[36:39]
	v_mfma_f32_16x16x32_bf16 v[32:35], v[184:187], v[204:207], v[32:35]
	v_mfma_f32_16x16x32_bf16 v[20:23], v[176:179], v[212:215], v[20:23]
	v_mfma_f32_16x16x32_bf16 v[16:19], v[184:187], v[212:215], v[16:19]
	v_mfma_f32_16x16x32_bf16 v[4:7], v[176:179], v[220:223], v[4:7]
	v_mfma_f32_16x16x32_bf16 v[0:3], v[184:187], v[220:223], v[0:3]
	v_mfma_f32_16x16x32_bf16 v[52:55], v[180:183], v[196:199], v[52:55]
	v_mfma_f32_16x16x32_bf16 v[48:51], v[188:191], v[196:199], v[48:51]
	v_mfma_f32_16x16x32_bf16 v[36:39], v[180:183], v[208:211], v[36:39]
	v_mfma_f32_16x16x32_bf16 v[32:35], v[188:191], v[208:211], v[32:35]
	v_mfma_f32_16x16x32_bf16 v[20:23], v[180:183], v[216:219], v[20:23]
	v_mfma_f32_16x16x32_bf16 v[16:19], v[188:191], v[216:219], v[16:19]
	v_mfma_f32_16x16x32_bf16 v[4:7], v[180:183], v[224:227], v[4:7]
	v_mfma_f32_16x16x32_bf16 v[0:3], v[188:191], v[224:227], v[0:3]
	s_setprio 0
	s_barrier
	s_add_i32 s51, s51, 2
	s_add_u32 s86, s86, 0x100
	s_addc_u32 s87, s87, 0
	s_add_u32 s27, s27, 0x100
	s_addc_u32 s50, s50, 0
	s_cmp_gt_u32 s51, 29

; #define PG8_STAGE(bufoff, gbase, voff) do { _Pragma("unroll") for (int _i = 0; _i < 2; ++_i) \
;         __builtin_amdgcn_global_load_lds((const unsigned*)((const char*)(gbase) + (voff)[_i]), (LAS unsigned*)(lds + (bufoff) + ldsw + _i * 8192), 16, 0, 0); } while (0)
; #define PG8_LDA(dst, b, h) do { _Pragma("unroll") for (int m = 0; m < 4; ++m) _Pragma("unroll") for (int k = 0; k < 2; ++k) dst[m][k] = *(const LAS bf16x8*)(lds + PG8_SA(b, h) + aoff + m * 2048 + k * 1024); } while (0)
; #define PG8_LDB(dst, b, h) do { _Pragma("unroll") for (int n = 0; n < 2; ++n) _Pragma("unroll") for (int k = 0; k < 2; ++k) dst[n][k] = *(const LAS bf16x8*)(lds + PG8_SB(b, h) + boff + n * 2048 + k * 1024); } while (0)
; #define PG8_MMA(ai, bj, At, Bt) do { __builtin_amdgcn_s_setprio(1); _Pragma("unroll") for (int m = 0; m < 4; ++m) _Pragma("unroll") for (int n = 0; n < 2; ++n) _Pragma("unroll") for (int k = 0; k < 2; ++k) \
;         acc[ai][bj][m][n] = __builtin_amdgcn_mfma_f32_16x16x32_bf16(Bt[n][k], At[m][k], acc[ai][bj][m][n], 0, 0, 0); __builtin_amdgcn_s_setprio(0); } while (0)
; #define PG8_BAR __builtin_amdgcn_s_barrier()
; template <class Epi, bool ALIGN_EPI, class Hook = NoHook>
; __device__ __forceinline__ void gemm_phase(LAS unsigned char* lds, const Gemm g, const StaticOrder& S, const Epi& E, const Hook& HK = Hook()) {
;     ...
;         const bool has_next = S.next(ui + 1, nxt);
;         const char* nA = has_next ? (const char*)g.A + (size_t)nxt.pm * tstepA : cA; const char* nB = has_next ? (const char*)g.Bt + (size_t)nxt.pn * tstepB : cB;
;         for (int t = 0; t < nt; t += 2) {
;             if (Hook::AT > 0 && t == Hook::AT) HK(acc, cur, wr, wc, fr, fq);
;             const bool last = (t == nt - 2);
;             const char* a1 = cA + (size_t)(t + 1) * kstep;
;             const char* a2 = last ? nA : cA + (size_t)(t + 2) * kstep; const char* b2 = last ? nB : cB + (size_t)(t + 2) * kstep;
;             const char* a3 = a2 + kstep; const char* b3 = b2 + kstep;
;             PG8_LDB(B0, 0, 0); PG8_LDB(B1, 0, 1); PG8_SCHED; PG8_LDA(At, 0, 0); PG8_STAGE(PG8_SA(1, 1), a1 + hstepA, voffA);
;             PG8_WAIT_V(8); PG8_WAIT_L(0); PG8_BAR; PG8_MMA(0, 0, At, B0); PG8_MMA(0, 1, At, B1); PG8_BAR; PG8_SCHED;
;             PG8_LDA(At, 0, 1); PG8_STAGE(PG8_SB(0, 0), b2, voffB); PG8_STAGE(PG8_SB(0, 1), b2 + hstepB, voffB); PG8_STAGE(PG8_SA(0, 0), a2, voffA);
.LBB0_786:
	s_ashr_i32 s23, s22, 31
	s_lshl_b64 s[24:25], s[22:23], 20
	s_add_u32 s24, s66, s24
	s_addc_u32 s25, s67, s25
	s_and_b64 s[34:35], s[0:1], exec
	s_cselect_b32 s23, s25, s41
	s_cselect_b32 s81, s24, s40
	s_ashr_i32 s21, s20, 31
	s_lshl_b64 s[34:35], s[20:21], 20
	s_add_u32 s36, s74, s34
	s_addc_u32 s37, s75, s35
	s_and_b64 s[34:35], s[0:1], exec
	s_cselect_b32 s21, s37, s43
	s_cselect_b32 s82, s36, s42
	s_add_u32 s40, s40, 0x80080
	s_addc_u32 s41, s41, 0
	s_add_u32 s83, s42, 0x100
	s_addc_u32 s84, s43, 0
	s_mov_b32 s85, -2
	s_waitcnt vmcnt(0)
	ds_read_b128 v[152:155], v165
	ds_read_b128 v[156:159], v165 offset:1024
	ds_read_b128 v[160:163], v165 offset:2048
	ds_read_b128 v[168:171], v165 offset:3072
	ds_read_b128 v[172:175], v166
	ds_read_b128 v[176:179], v166 offset:1024
	ds_read_b128 v[180:183], v166 offset:2048
	ds_read_b128 v[184:187], v166 offset:3072
	s_add_u32 s34, s40, 0xfff80080
	s_addc_u32 s35, s41, -1
	s_cmp_eq_u32 s85, 28
	s_cselect_b32 s45, s23, s35
	s_cselect_b32 s44, s81, s34
	s_cselect_b32 s43, s21, s84
	s_cselect_b32 s42, s82, s83
	v_lshl_add_u64 v[228:229], s[40:41], 0, v[144:145]
	s_add_i32 m0, s28, 0xc000
	ds_read_b128 v[188:191], v167
	ds_read_b128 v[192:195], v167 offset:1024
	ds_read_b128 v[196:199], v167 offset:2048
	ds_read_b128 v[208:211], v167 offset:3072
	ds_read_b128 v[212:215], v167 offset:4096
	ds_read_b128 v[216:219], v167 offset:5120
	ds_read_b128 v[220:223], v167 offset:6144
	ds_read_b128 v[224:227], v167 offset:7168
	global_load_lds_dwordx4 v[228:229], off
	v_lshl_add_u64 v[228:229], s[40:41], 0, v[146:147]
	s_add_i32 m0, s28, 0xe000
	s_nop 0
	global_load_lds_dwordx4 v[228:229], off
	s_waitcnt vmcnt(8)
	s_waitcnt lgkmcnt(0)
	s_barrier
	s_setprio 1
	s_waitcnt lgkmcnt(0)
	v_mfma_f32_16x16x32_bf16 v[124:127], v[152:155], v[188:191], 0
	v_mfma_f32_16x16x32_bf16 v[120:123], v[160:163], v[188:191], 0
	v_mfma_f32_16x16x32_bf16 v[112:115], v[152:155], v[196:199], 0
	v_mfma_f32_16x16x32_bf16 v[104:107], v[160:163], v[196:199], 0
	v_mfma_f32_16x16x32_bf16 v[96:99], v[152:155], v[212:215], 0
	v_mfma_f32_16x16x32_bf16 v[88:91], v[160:163], v[212:215], 0
	v_mfma_f32_16x16x32_bf16 v[80:83], v[152:155], v[220:223], 0
	v_mfma_f32_16x16x32_bf16 v[72:75], v[160:163], v[220:223], 0
	v_mfma_f32_16x16x32_bf16 v[124:127], v[156:159], v[192:195], v[124:127]
	v_mfma_f32_16x16x32_bf16 v[120:123], v[168:171], v[192:195], v[120:123]
	v_mfma_f32_16x16x32_bf16 v[112:115], v[156:159], v[208:211], v[112:115]
	v_mfma_f32_16x16x32_bf16 v[104:107], v[168:171], v[208:211], v[104:107]
	v_mfma_f32_16x16x32_bf16 v[96:99], v[156:159], v[216:219], v[96:99]
	v_mfma_f32_16x16x32_bf16 v[88:91], v[168:171], v[216:219], v[88:91]
	v_mfma_f32_16x16x32_bf16 v[80:83], v[156:159], v[224:227], v[80:83]
	v_mfma_f32_16x16x32_bf16 v[72:75], v[168:171], v[224:227], v[72:75]
	s_setprio 0
	s_setprio 1
	v_mfma_f32_16x16x32_bf16 v[116:119], v[172:175], v[188:191], 0
	v_mfma_f32_16x16x32_bf16 v[108:111], v[180:183], v[188:191], 0
	v_mfma_f32_16x16x32_bf16 v[100:103], v[172:175], v[196:199], 0
	v_mfma_f32_16x16x32_bf16 v[92:95], v[180:183], v[196:199], 0
	v_mfma_f32_16x16x32_bf16 v[84:87], v[172:175], v[212:215], 0
	v_mfma_f32_16x16x32_bf16 v[76:79], v[180:183], v[212:215], 0
	v_mfma_f32_16x16x32_bf16 v[68:71], v[172:175], v[220:223], 0
	v_mfma_f32_16x16x32_bf16 v[64:67], v[180:183], v[220:223], 0
	v_mfma_f32_16x16x32_bf16 v[116:119], v[176:179], v[192:195], v[116:119]
	v_mfma_f32_16x16x32_bf16 v[108:111], v[184:187], v[192:195], v[108:111]
	v_mfma_f32_16x16x32_bf16 v[100:103], v[176:179], v[208:211], v[100:103]
	v_mfma_f32_16x16x32_bf16 v[92:95], v[184:187], v[208:211], v[92:95]
	v_mfma_f32_16x16x32_bf16 v[84:87], v[176:179], v[216:219], v[84:87]
	v_mfma_f32_16x16x32_bf16 v[76:79], v[184:187], v[216:219], v[76:79]
	v_mfma_f32_16x16x32_bf16 v[68:71], v[176:179], v[224:227], v[68:71]
	v_mfma_f32_16x16x32_bf16 v[64:67], v[184:187], v[224:227], v[64:67]
	s_setprio 0
	s_barrier
	s_add_i32 s34, s78, s27
	v_lshl_add_u64 v[228:229], s[42:43], 0, v[130:131]
	s_mov_b32 m0, s34
	ds_read_b128 v[188:191], v167 offset:16384
	ds_read_b128 v[192:195], v167 offset:17408
	ds_read_b128 v[196:199], v167 offset:18432
	ds_read_b128 v[208:211], v167 offset:19456
	ds_read_b128 v[212:215], v167 offset:20480
	ds_read_b128 v[216:219], v167 offset:21504
	ds_read_b128 v[220:223], v167 offset:22528
	ds_read_b128 v[224:227], v167 offset:23552
	global_load_lds_dwordx4 v[228:229], off
	s_add_i32 m0, s34, 0x2000
	s_add_u32 s34, s42, 0x80000
	v_lshl_add_u64 v[230:231], s[42:43], 0, v[134:135]
	s_addc_u32 s35, s43, 0
	s_add_i32 s52, s79, s27
	global_load_lds_dwordx4 v[230:231], off
	v_lshl_add_u64 v[232:233], s[34:35], 0, v[130:131]
	s_mov_b32 m0, s52
	v_lshl_add_u64 v[234:235], s[44:45], 0, v[132:133]
	global_load_lds_dwordx4 v[232:233], off
	v_lshl_add_u64 v[232:233], s[34:35], 0, v[134:135]
	s_add_i32 m0, s52, 0x2000
	s_nop 0
	global_load_lds_dwordx4 v[232:233], off
	v_lshl_add_u64 v[232:233], s[44:45], 0, v[128:129]
	s_mov_b32 m0, s28
	s_nop 0
	global_load_lds_dwordx4 v[232:233], off
	s_mov_b32 m0, s29
	s_nop 0
	global_load_lds_dwordx4 v[234:235], off
	s_waitcnt vmcnt(8)
	s_waitcnt lgkmcnt(0)
	s_barrier
; #define PG8_STAGE(bufoff, gbase, voff) do { _Pragma("unroll") for (int _i = 0; _i < 2; ++_i) \
;         __builtin_amdgcn_global_load_lds((const unsigned*)((const char*)(gbase) + (voff)[_i]), (LAS unsigned*)(lds + (bufoff) + ldsw + _i * 8192), 16, 0, 0); } while (0)
; #define PG8_LDA(dst, b, h) do { _Pragma("unroll") for (int m = 0; m < 4; ++m) _Pragma("unroll") for (int k = 0; k < 2; ++k) dst[m][k] = *(const LAS bf16x8*)(lds + PG8_SA(b, h) + aoff + m * 2048 + k * 1024); } while (0)
; #define PG8_LDB(dst, b, h) do { _Pragma("unroll") for (int n = 0; n < 2; ++n) _Pragma("unroll") for (int k = 0; k < 2; ++k) dst[n][k] = *(const LAS bf16x8*)(lds + PG8_SB(b, h) + boff + n * 2048 + k * 1024); } while (0)
; #define PG8_MMA(ai, bj, At, Bt) do { __builtin_amdgcn_s_setprio(1); _Pragma("unroll") for (int m = 0; m < 4; ++m) _Pragma("unroll") for (int n = 0; n < 2; ++n) _Pragma("unroll") for (int k = 0; k < 2; ++k) \
;         acc[ai][bj][m][n] = __builtin_amdgcn_mfma_f32_16x16x32_bf16(Bt[n][k], At[m][k], acc[ai][bj][m][n], 0, 0, 0); __builtin_amdgcn_s_setprio(0); } while (0)
; #define PG8_WAIT_V(n) asm volatile("s_waitcnt vmcnt(" #n ")" ::: "memory")
; #define PG8_WAIT_L(n) asm volatile("s_waitcnt lgkmcnt(" #n ")" ::: "memory")
; #define PG8_BAR __builtin_amdgcn_s_barrier()
; #define PG8_SCHED __builtin_amdgcn_sched_barrier(0)
; template <class Epi, bool ALIGN_EPI, class Hook = NoHook>
; __device__ __forceinline__ void gemm_phase(LAS unsigned char* lds, const Gemm g, const StaticOrder& S, const Epi& E, const Hook& HK = Hook()) {
;     ...
;             PG8_WAIT_V(8); PG8_WAIT_L(0); PG8_BAR; PG8_MMA(1, 0, At, B0); PG8_MMA(1, 1, At, B1); PG8_BAR; PG8_SCHED;
;             PG8_LDB(B0, 1, 0); PG8_LDB(B1, 1, 1); PG8_SCHED; PG8_LDA(At, 1, 0); PG8_STAGE(PG8_SA(0, 1), a2 + hstepA, voffA);
;             PG8_WAIT_V(8); PG8_WAIT_L(0); PG8_BAR; PG8_MMA(0, 0, At, B0); PG8_MMA(0, 1, At, B1); PG8_BAR; PG8_SCHED;
	s_setprio 1
	s_waitcnt lgkmcnt(0)
	v_mfma_f32_16x16x32_bf16 v[60:63], v[152:155], v[188:191], 0
	v_mfma_f32_16x16x32_bf16 v[56:59], v[160:163], v[188:191], 0
	v_mfma_f32_16x16x32_bf16 v[48:51], v[152:155], v[196:199], 0
	v_mfma_f32_16x16x32_bf16 v[40:43], v[160:163], v[196:199], 0
	v_mfma_f32_16x16x32_bf16 v[32:35], v[152:155], v[212:215], 0
	v_mfma_f32_16x16x32_bf16 v[24:27], v[160:163], v[212:215], 0
	v_mfma_f32_16x16x32_bf16 v[16:19], v[152:155], v[220:223], 0
	v_mfma_f32_16x16x32_bf16 v[8:11], v[160:163], v[220:223], 0
	v_mfma_f32_16x16x32_bf16 v[60:63], v[156:159], v[192:195], v[60:63]
	v_mfma_f32_16x16x32_bf16 v[56:59], v[168:171], v[192:195], v[56:59]
	v_mfma_f32_16x16x32_bf16 v[48:51], v[156:159], v[208:211], v[48:51]
	v_mfma_f32_16x16x32_bf16 v[40:43], v[168:171], v[208:211], v[40:43]
	v_mfma_f32_16x16x32_bf16 v[32:35], v[156:159], v[216:219], v[32:35]
	v_mfma_f32_16x16x32_bf16 v[24:27], v[168:171], v[216:219], v[24:27]
	v_mfma_f32_16x16x32_bf16 v[16:19], v[156:159], v[224:227], v[16:19]
	v_mfma_f32_16x16x32_bf16 v[8:11], v[168:171], v[224:227], v[8:11]
	s_setprio 0
	s_setprio 1
	v_mfma_f32_16x16x32_bf16 v[52:55], v[172:175], v[188:191], 0
	v_mfma_f32_16x16x32_bf16 v[44:47], v[180:183], v[188:191], 0
	v_mfma_f32_16x16x32_bf16 v[36:39], v[172:175], v[196:199], 0
	v_mfma_f32_16x16x32_bf16 v[28:31], v[180:183], v[196:199], 0
	v_mfma_f32_16x16x32_bf16 v[20:23], v[172:175], v[212:215], 0
	v_mfma_f32_16x16x32_bf16 v[12:15], v[180:183], v[212:215], 0
	v_mfma_f32_16x16x32_bf16 v[4:7], v[172:175], v[220:223], 0
	v_mfma_f32_16x16x32_bf16 v[0:3], v[180:183], v[220:223], 0
	v_mfma_f32_16x16x32_bf16 v[52:55], v[176:179], v[192:195], v[52:55]
	v_mfma_f32_16x16x32_bf16 v[44:47], v[184:187], v[192:195], v[44:47]
	v_mfma_f32_16x16x32_bf16 v[36:39], v[176:179], v[208:211], v[36:39]
	v_mfma_f32_16x16x32_bf16 v[28:31], v[184:187], v[208:211], v[28:31]
	v_mfma_f32_16x16x32_bf16 v[20:23], v[176:179], v[216:219], v[20:23]
	v_mfma_f32_16x16x32_bf16 v[12:15], v[184:187], v[216:219], v[12:15]
	v_mfma_f32_16x16x32_bf16 v[4:7], v[176:179], v[224:227], v[4:7]
	v_mfma_f32_16x16x32_bf16 v[0:3], v[184:187], v[224:227], v[0:3]
	s_setprio 0
	s_barrier
	s_add_i32 s52, 0, 0x18000
	s_add_i32 s53, 0, 0x1c000
	v_add_u32_e32 v168, s52, v143
	v_add_u32_e32 v184, s53, v143
	ds_read_b128 v[152:155], v168
	ds_read_b128 v[156:159], v168 offset:1024
	ds_read_b128 v[160:163], v168 offset:2048
	ds_read_b128 v[168:171], v168 offset:3072
	ds_read_b128 v[172:175], v184
	ds_read_b128 v[176:179], v184 offset:1024
	ds_read_b128 v[180:183], v184 offset:2048
	ds_read_b128 v[184:187], v184 offset:3072
	s_add_u32 s34, s44, 0x80000
	s_addc_u32 s35, s45, 0
	s_mov_b32 m0, s39
	v_lshl_add_u64 v[236:237], s[34:35], 0, v[128:129]
	ds_read_b128 v[188:191], v167 offset:32768
	ds_read_b128 v[192:195], v167 offset:33792
	ds_read_b128 v[196:199], v167 offset:34816
	ds_read_b128 v[208:211], v167 offset:35840
	ds_read_b128 v[212:215], v167 offset:36864
	ds_read_b128 v[216:219], v167 offset:37888
	ds_read_b128 v[220:223], v167 offset:38912
	ds_read_b128 v[224:227], v167 offset:39936
	global_load_lds_dwordx4 v[236:237], off
	v_lshl_add_u64 v[236:237], s[34:35], 0, v[132:133]
	s_mov_b32 m0, s50
	s_nop 0
	global_load_lds_dwordx4 v[236:237], off
	s_waitcnt vmcnt(8)
	s_waitcnt lgkmcnt(0)
	s_barrier
	s_setprio 1
	s_waitcnt lgkmcnt(0)
	v_mfma_f32_16x16x32_bf16 v[124:127], v[152:155], v[188:191], v[124:127]
	v_mfma_f32_16x16x32_bf16 v[120:123], v[160:163], v[188:191], v[120:123]
	v_mfma_f32_16x16x32_bf16 v[112:115], v[152:155], v[196:199], v[112:115]
	v_mfma_f32_16x16x32_bf16 v[104:107], v[160:163], v[196:199], v[104:107]
	v_mfma_f32_16x16x32_bf16 v[96:99], v[152:155], v[212:215], v[96:99]
	v_mfma_f32_16x16x32_bf16 v[88:91], v[160:163], v[212:215], v[88:91]
	v_mfma_f32_16x16x32_bf16 v[80:83], v[152:155], v[220:223], v[80:83]
	v_mfma_f32_16x16x32_bf16 v[72:75], v[160:163], v[220:223], v[72:75]
	v_mfma_f32_16x16x32_bf16 v[124:127], v[156:159], v[192:195], v[124:127]
	v_mfma_f32_16x16x32_bf16 v[120:123], v[168:171], v[192:195], v[120:123]
	v_mfma_f32_16x16x32_bf16 v[112:115], v[156:159], v[208:211], v[112:115]
	v_mfma_f32_16x16x32_bf16 v[104:107], v[168:171], v[208:211], v[104:107]
	v_mfma_f32_16x16x32_bf16 v[96:99], v[156:159], v[216:219], v[96:99]
	v_mfma_f32_16x16x32_bf16 v[88:91], v[168:171], v[216:219], v[88:91]
	v_mfma_f32_16x16x32_bf16 v[80:83], v[156:159], v[224:227], v[80:83]
	v_mfma_f32_16x16x32_bf16 v[72:75], v[168:171], v[224:227], v[72:75]
	s_setprio 0
	s_setprio 1
	v_mfma_f32_16x16x32_bf16 v[116:119], v[172:175], v[188:191], v[116:119]
	v_mfma_f32_16x16x32_bf16 v[108:111], v[180:183], v[188:191], v[108:111]
	v_mfma_f32_16x16x32_bf16 v[100:103], v[172:175], v[196:199], v[100:103]
	v_mfma_f32_16x16x32_bf16 v[92:95], v[180:183], v[196:199], v[92:95]
	v_mfma_f32_16x16x32_bf16 v[84:87], v[172:175], v[212:215], v[84:87]
	v_mfma_f32_16x16x32_bf16 v[76:79], v[180:183], v[212:215], v[76:79]
	v_mfma_f32_16x16x32_bf16 v[68:71], v[172:175], v[220:223], v[68:71]
	v_mfma_f32_16x16x32_bf16 v[64:67], v[180:183], v[220:223], v[64:67]
	v_mfma_f32_16x16x32_bf16 v[116:119], v[176:179], v[192:195], v[116:119]
	v_mfma_f32_16x16x32_bf16 v[108:111], v[184:187], v[192:195], v[108:111]
	v_mfma_f32_16x16x32_bf16 v[100:103], v[176:179], v[208:211], v[100:103]
	v_mfma_f32_16x16x32_bf16 v[92:95], v[184:187], v[208:211], v[92:95]
	v_mfma_f32_16x16x32_bf16 v[84:87], v[176:179], v[216:219], v[84:87]
	v_mfma_f32_16x16x32_bf16 v[76:79], v[184:187], v[216:219], v[76:79]
	v_mfma_f32_16x16x32_bf16 v[68:71], v[176:179], v[224:227], v[68:71]
	v_mfma_f32_16x16x32_bf16 v[64:67], v[184:187], v[224:227], v[64:67]
	s_setprio 0
	s_barrier
; #define PG8_STAGE(bufoff, gbase, voff) do { _Pragma("unroll") for (int _i = 0; _i < 2; ++_i) \
;         __builtin_amdgcn_global_load_lds((const unsigned*)((const char*)(gbase) + (voff)[_i]), (LAS unsigned*)(lds + (bufoff) + ldsw + _i * 8192), 16, 0, 0); } while (0)
; #define PG8_LDA(dst, b, h) do { _Pragma("unroll") for (int m = 0; m < 4; ++m) _Pragma("unroll") for (int k = 0; k < 2; ++k) dst[m][k] = *(const LAS bf16x8*)(lds + PG8_SA(b, h) + aoff + m * 2048 + k * 1024); } while (0)
; #define PG8_MMA(ai, bj, At, Bt) do { __builtin_amdgcn_s_setprio(1); _Pragma("unroll") for (int m = 0; m < 4; ++m) _Pragma("unroll") for (int n = 0; n < 2; ++n) _Pragma("unroll") for (int k = 0; k < 2; ++k) \
;         acc[ai][bj][m][n] = __builtin_amdgcn_mfma_f32_16x16x32_bf16(Bt[n][k], At[m][k], acc[ai][bj][m][n], 0, 0, 0); __builtin_amdgcn_s_setprio(0); } while (0)
; #define PG8_WAIT_V(n) asm volatile("s_waitcnt vmcnt(" #n ")" ::: "memory")
; #define PG8_WAIT_L(n) asm volatile("s_waitcnt lgkmcnt(" #n ")" ::: "memory")
; #define PG8_BAR __builtin_amdgcn_s_barrier()
; #define PG8_SCHED __builtin_amdgcn_sched_barrier(0)
; template <class Epi, bool ALIGN_EPI, class Hook = NoHook>
; __device__ __forceinline__ void gemm_phase(LAS unsigned char* lds, const Gemm g, const StaticOrder& S, const Epi& E, const Hook& HK = Hook()) {
;     ...
;             PG8_LDA(At, 1, 1); PG8_STAGE(PG8_SB(1, 0), b3, voffB); PG8_STAGE(PG8_SB(1, 1), b3 + hstepB, voffB); PG8_STAGE(PG8_SA(1, 0), a3, voffA);
;             PG8_WAIT_V(8); PG8_WAIT_L(0); PG8_BAR; PG8_MMA(1, 0, At, B0); PG8_MMA(1, 1, At, B1); PG8_BAR; PG8_SCHED;
	s_add_i32 s34, s52, s27
	v_lshl_add_u64 v[228:229], v[228:229], 0, s[10:11]
	s_mov_b32 m0, s34
	ds_read_b128 v[188:191], v167 offset:49152
	ds_read_b128 v[192:195], v167 offset:50176
	ds_read_b128 v[196:199], v167 offset:51200
	ds_read_b128 v[208:211], v167 offset:52224
	ds_read_b128 v[212:215], v167 offset:53248
	ds_read_b128 v[216:219], v167 offset:54272
	ds_read_b128 v[220:223], v167 offset:55296
	ds_read_b128 v[224:227], v167 offset:56320
	global_load_lds_dwordx4 v[228:229], off
	s_add_i32 m0, s34, 0x2000
	s_add_u32 s34, s42, 0x80080
	v_lshl_add_u64 v[228:229], v[230:231], 0, s[10:11]
	s_addc_u32 s35, s43, 0
	s_add_i32 s42, s53, s27
	global_load_lds_dwordx4 v[228:229], off
	v_lshl_add_u64 v[228:229], s[34:35], 0, v[130:131]
	s_mov_b32 m0, s42
	s_nop 0
	global_load_lds_dwordx4 v[228:229], off
	v_lshl_add_u64 v[228:229], s[34:35], 0, v[134:135]
	s_add_i32 m0, s42, 0x2000
	s_nop 0
	global_load_lds_dwordx4 v[228:229], off
	v_lshl_add_u64 v[228:229], v[232:233], 0, s[10:11]
	s_mov_b32 m0, s65
	s_nop 0
	global_load_lds_dwordx4 v[228:229], off
	v_lshl_add_u64 v[228:229], v[234:235], 0, s[10:11]
	s_mov_b32 m0, s71
	s_nop 0
	global_load_lds_dwordx4 v[228:229], off
	s_waitcnt vmcnt(8)
	s_waitcnt lgkmcnt(0)
	s_barrier
	s_setprio 1
	s_waitcnt lgkmcnt(0)
	v_mfma_f32_16x16x32_bf16 v[60:63], v[152:155], v[188:191], v[60:63]
	v_mfma_f32_16x16x32_bf16 v[56:59], v[160:163], v[188:191], v[56:59]
	v_mfma_f32_16x16x32_bf16 v[48:51], v[152:155], v[196:199], v[48:51]
	v_mfma_f32_16x16x32_bf16 v[40:43], v[160:163], v[196:199], v[40:43]
	v_mfma_f32_16x16x32_bf16 v[32:35], v[152:155], v[212:215], v[32:35]
	v_mfma_f32_16x16x32_bf16 v[24:27], v[160:163], v[212:215], v[24:27]
	v_mfma_f32_16x16x32_bf16 v[16:19], v[152:155], v[220:223], v[16:19]
	v_mfma_f32_16x16x32_bf16 v[8:11], v[160:163], v[220:223], v[8:11]
	v_mfma_f32_16x16x32_bf16 v[60:63], v[156:159], v[192:195], v[60:63]
	v_mfma_f32_16x16x32_bf16 v[56:59], v[168:171], v[192:195], v[56:59]
	v_mfma_f32_16x16x32_bf16 v[48:51], v[156:159], v[208:211], v[48:51]
	v_mfma_f32_16x16x32_bf16 v[40:43], v[168:171], v[208:211], v[40:43]
	v_mfma_f32_16x16x32_bf16 v[32:35], v[156:159], v[216:219], v[32:35]
	v_mfma_f32_16x16x32_bf16 v[24:27], v[168:171], v[216:219], v[24:27]
	v_mfma_f32_16x16x32_bf16 v[16:19], v[156:159], v[224:227], v[16:19]
	v_mfma_f32_16x16x32_bf16 v[8:11], v[168:171], v[224:227], v[8:11]
	s_setprio 0
	s_setprio 1
	v_mfma_f32_16x16x32_bf16 v[52:55], v[172:175], v[188:191], v[52:55]
	v_mfma_f32_16x16x32_bf16 v[44:47], v[180:183], v[188:191], v[44:47]
	v_mfma_f32_16x16x32_bf16 v[36:39], v[172:175], v[196:199], v[36:39]
	v_mfma_f32_16x16x32_bf16 v[28:31], v[180:183], v[196:199], v[28:31]
	v_mfma_f32_16x16x32_bf16 v[20:23], v[172:175], v[212:215], v[20:23]
	v_mfma_f32_16x16x32_bf16 v[12:15], v[180:183], v[212:215], v[12:15]
	v_mfma_f32_16x16x32_bf16 v[4:7], v[172:175], v[220:223], v[4:7]
	v_mfma_f32_16x16x32_bf16 v[0:3], v[180:183], v[220:223], v[0:3]
	v_mfma_f32_16x16x32_bf16 v[52:55], v[176:179], v[192:195], v[52:55]
	v_mfma_f32_16x16x32_bf16 v[44:47], v[184:187], v[192:195], v[44:47]
	v_mfma_f32_16x16x32_bf16 v[36:39], v[176:179], v[208:211], v[36:39]
	v_mfma_f32_16x16x32_bf16 v[28:31], v[184:187], v[208:211], v[28:31]
	v_mfma_f32_16x16x32_bf16 v[20:23], v[176:179], v[216:219], v[20:23]
	v_mfma_f32_16x16x32_bf16 v[12:15], v[184:187], v[216:219], v[12:15]
	v_mfma_f32_16x16x32_bf16 v[4:7], v[176:179], v[224:227], v[4:7]
	v_mfma_f32_16x16x32_bf16 v[0:3], v[184:187], v[224:227], v[0:3]
	s_setprio 0
	s_barrier
	s_add_i32 s85, s85, 2
	s_add_u32 s40, s40, 0x100
	s_addc_u32 s41, s41, 0
	s_add_u32 s83, s83, 0x100
	s_addc_u32 s84, s84, 0
	s_cmp_gt_u32 s85, 29

; #define PG8_STAGE(bufoff, gbase, voff) do { _Pragma("unroll") for (int _i = 0; _i < 2; ++_i) \
;         __builtin_amdgcn_global_load_lds((const unsigned*)((const char*)(gbase) + (voff)[_i]), (LAS unsigned*)(lds + (bufoff) + ldsw + _i * 8192), 16, 0, 0); } while (0)
; #define PG8_LDA(dst, b, h) do { _Pragma("unroll") for (int m = 0; m < 4; ++m) _Pragma("unroll") for (int k = 0; k < 2; ++k) dst[m][k] = *(const LAS bf16x8*)(lds + PG8_SA(b, h) + aoff + m * 2048 + k * 1024); } while (0)
; #define PG8_LDB(dst, b, h) do { _Pragma("unroll") for (int n = 0; n < 2; ++n) _Pragma("unroll") for (int k = 0; k < 2; ++k) dst[n][k] = *(const LAS bf16x8*)(lds + PG8_SB(b, h) + boff + n * 2048 + k * 1024); } while (0)
; #define PG8_MMA(ai, bj, At, Bt) do { __builtin_amdgcn_s_setprio(1); _Pragma("unroll") for (int m = 0; m < 4; ++m) _Pragma("unroll") for (int n = 0; n < 2; ++n) _Pragma("unroll") for (int k = 0; k < 2; ++k) \
;         acc[ai][bj][m][n] = __builtin_amdgcn_mfma_f32_16x16x32_bf16(Bt[n][k], At[m][k], acc[ai][bj][m][n], 0, 0, 0); __builtin_amdgcn_s_setprio(0); } while (0)
; #define PG8_BAR __builtin_amdgcn_s_barrier()
; template <class Epi, bool ALIGN_EPI, class Hook = NoHook>
; __device__ __forceinline__ void gemm_phase(LAS unsigned char* lds, const Gemm g, const StaticOrder& S, const Epi& E, const Hook& HK = Hook()) {
;     ...
;         const bool has_next = S.next(ui + 1, nxt);
;         const char* nA = has_next ? (const char*)g.A + (size_t)nxt.pm * tstepA : cA; const char* nB = has_next ? (const char*)g.Bt + (size_t)nxt.pn * tstepB : cB;
;         for (int t = 0; t < nt; t += 2) {
;             if (Hook::AT > 0 && t == Hook::AT) HK(acc, cur, wr, wc, fr, fq);
;             const bool last = (t == nt - 2);
;             const char* a1 = cA + (size_t)(t + 1) * kstep;
;             const char* a2 = last ? nA : cA + (size_t)(t + 2) * kstep; const char* b2 = last ? nB : cB + (size_t)(t + 2) * kstep;
;             const char* a3 = a2 + kstep; const char* b3 = b2 + kstep;
;             PG8_LDB(B0, 0, 0); PG8_LDB(B1, 0, 1); PG8_SCHED; PG8_LDA(At, 0, 0); PG8_STAGE(PG8_SA(1, 1), a1 + hstepA, voffA);
;             PG8_WAIT_V(8); PG8_WAIT_L(0); PG8_BAR; PG8_MMA(0, 0, At, B0); PG8_MMA(0, 1, At, B1); PG8_BAR; PG8_SCHED;
;             PG8_LDA(At, 0, 1); PG8_STAGE(PG8_SB(0, 0), b2, voffB); PG8_STAGE(PG8_SB(0, 1), b2 + hstepB, voffB); PG8_STAGE(PG8_SA(0, 0), a2, voffA);
.LBB0_918:
	s_ashr_i32 s17, s16, 31
	s_lshl_b64 s[18:19], s[16:17], 20
	s_add_u32 s18, s48, s18
	s_addc_u32 s19, s49, s19
	s_and_b64 s[20:21], s[0:1], exec
	s_cselect_b32 s17, s19, s25
	s_cselect_b32 s53, s18, s24
	s_ashr_i32 s15, s14, 31
	s_lshl_b64 s[20:21], s[14:15], 20
	s_add_u32 s20, s66, s20
	s_addc_u32 s21, s67, s21
	s_and_b64 s[34:35], s[0:1], exec
	s_cselect_b32 s15, s21, s29
	s_cselect_b32 s54, s20, s28
	s_add_u32 s24, s24, 0x80080
	s_addc_u32 s25, s25, 0
	s_add_u32 s55, s28, 0x100
	s_addc_u32 s56, s29, 0
	s_mov_b32 s57, -2
	ds_read_b128 v[146:149], v152
	ds_read_b128 v[156:159], v152 offset:1024
	ds_read_b128 v[160:163], v152 offset:2048
	ds_read_b128 v[164:167], v152 offset:3072
	ds_read_b128 v[168:171], v153
	ds_read_b128 v[172:175], v153 offset:1024
	ds_read_b128 v[176:179], v153 offset:2048
	ds_read_b128 v[180:183], v153 offset:3072
	s_add_u32 s28, s24, 0xfff80080
	s_addc_u32 s29, s25, -1
	s_cmp_eq_u32 s57, 28
	s_cselect_b32 s37, s17, s29
	s_cselect_b32 s36, s53, s28
	s_cselect_b32 s29, s15, s56
	s_cselect_b32 s28, s54, s55
	v_lshl_add_u64 v[216:217], s[24:25], 0, v[138:139]
	s_add_i32 m0, s23, 0xc000
	ds_read_b128 v[184:187], v154
	ds_read_b128 v[188:191], v154 offset:1024
	ds_read_b128 v[192:195], v154 offset:2048
	ds_read_b128 v[196:199], v154 offset:3072
	ds_read_b128 v[200:203], v154 offset:4096
	ds_read_b128 v[204:207], v154 offset:5120
	ds_read_b128 v[208:211], v154 offset:6144
	ds_read_b128 v[212:215], v154 offset:7168
	global_load_lds_dwordx4 v[216:217], off
	v_lshl_add_u64 v[216:217], s[24:25], 0, v[140:141]
	s_add_i32 m0, s23, 0xe000
	s_nop 0
	global_load_lds_dwordx4 v[216:217], off
	s_waitcnt vmcnt(8)
	s_waitcnt lgkmcnt(0)
	s_barrier
	s_setprio 1
	s_waitcnt lgkmcnt(0)
	v_mfma_f32_16x16x32_bf16 v[124:127], v[146:149], v[184:187], 0
	v_mfma_f32_16x16x32_bf16 v[120:123], v[160:163], v[184:187], 0
	v_mfma_f32_16x16x32_bf16 v[108:111], v[146:149], v[192:195], 0
	v_mfma_f32_16x16x32_bf16 v[104:107], v[160:163], v[192:195], 0
	v_mfma_f32_16x16x32_bf16 v[92:95], v[146:149], v[200:203], 0
	v_mfma_f32_16x16x32_bf16 v[88:91], v[160:163], v[200:203], 0
	v_mfma_f32_16x16x32_bf16 v[76:79], v[146:149], v[208:211], 0
	v_mfma_f32_16x16x32_bf16 v[72:75], v[160:163], v[208:211], 0
	v_mfma_f32_16x16x32_bf16 v[124:127], v[156:159], v[188:191], v[124:127]
	v_mfma_f32_16x16x32_bf16 v[120:123], v[164:167], v[188:191], v[120:123]
	v_mfma_f32_16x16x32_bf16 v[108:111], v[156:159], v[196:199], v[108:111]
	v_mfma_f32_16x16x32_bf16 v[104:107], v[164:167], v[196:199], v[104:107]
	v_mfma_f32_16x16x32_bf16 v[92:95], v[156:159], v[204:207], v[92:95]
	v_mfma_f32_16x16x32_bf16 v[88:91], v[164:167], v[204:207], v[88:91]
	v_mfma_f32_16x16x32_bf16 v[76:79], v[156:159], v[212:215], v[76:79]
	v_mfma_f32_16x16x32_bf16 v[72:75], v[164:167], v[212:215], v[72:75]
	s_setprio 0
	s_setprio 1
	v_mfma_f32_16x16x32_bf16 v[116:119], v[168:171], v[184:187], 0
	v_mfma_f32_16x16x32_bf16 v[112:115], v[176:179], v[184:187], 0
	v_mfma_f32_16x16x32_bf16 v[100:103], v[168:171], v[192:195], 0
	v_mfma_f32_16x16x32_bf16 v[96:99], v[176:179], v[192:195], 0
	v_mfma_f32_16x16x32_bf16 v[84:87], v[168:171], v[200:203], 0
	v_mfma_f32_16x16x32_bf16 v[80:83], v[176:179], v[200:203], 0
	v_mfma_f32_16x16x32_bf16 v[68:71], v[168:171], v[208:211], 0
	v_mfma_f32_16x16x32_bf16 v[64:67], v[176:179], v[208:211], 0
	v_mfma_f32_16x16x32_bf16 v[116:119], v[172:175], v[188:191], v[116:119]
	v_mfma_f32_16x16x32_bf16 v[112:115], v[180:183], v[188:191], v[112:115]
	v_mfma_f32_16x16x32_bf16 v[100:103], v[172:175], v[196:199], v[100:103]
	v_mfma_f32_16x16x32_bf16 v[96:99], v[180:183], v[196:199], v[96:99]
	v_mfma_f32_16x16x32_bf16 v[84:87], v[172:175], v[204:207], v[84:87]
	v_mfma_f32_16x16x32_bf16 v[80:83], v[180:183], v[204:207], v[80:83]
	v_mfma_f32_16x16x32_bf16 v[68:71], v[172:175], v[212:215], v[68:71]
	v_mfma_f32_16x16x32_bf16 v[64:67], v[180:183], v[212:215], v[64:67]
	s_setprio 0
	s_barrier
	s_add_i32 s34, s45, s13
	v_lshl_add_u64 v[216:217], s[28:29], 0, v[132:133]
	s_mov_b32 m0, s34
	ds_read_b128 v[184:187], v154 offset:16384
	ds_read_b128 v[188:191], v154 offset:17408
	ds_read_b128 v[192:195], v154 offset:18432
	ds_read_b128 v[196:199], v154 offset:19456
	ds_read_b128 v[200:203], v154 offset:20480
	ds_read_b128 v[204:207], v154 offset:21504
	ds_read_b128 v[208:211], v154 offset:22528
	ds_read_b128 v[212:215], v154 offset:23552
	global_load_lds_dwordx4 v[216:217], off
	s_add_i32 m0, s34, 0x2000
	s_add_u32 s34, s28, 0x80000
	v_lshl_add_u64 v[218:219], s[28:29], 0, v[128:129]
	s_addc_u32 s35, s29, 0
	s_add_i32 s58, s50, s13
	global_load_lds_dwordx4 v[218:219], off
	v_lshl_add_u64 v[220:221], s[34:35], 0, v[132:133]
	s_mov_b32 m0, s58
	v_lshl_add_u64 v[222:223], s[36:37], 0, v[130:131]
	global_load_lds_dwordx4 v[220:221], off
	v_lshl_add_u64 v[220:221], s[34:35], 0, v[128:129]
	s_add_i32 m0, s58, 0x2000
	s_nop 0
	global_load_lds_dwordx4 v[220:221], off
	v_lshl_add_u64 v[220:221], s[36:37], 0, v[134:135]
	s_mov_b32 m0, s23
	s_nop 0
	global_load_lds_dwordx4 v[220:221], off
	s_mov_b32 m0, s33
	s_nop 0
	global_load_lds_dwordx4 v[222:223], off
	s_waitcnt vmcnt(8)
	s_waitcnt lgkmcnt(0)
	s_barrier
; #define PG8_STAGE(bufoff, gbase, voff) do { _Pragma("unroll") for (int _i = 0; _i < 2; ++_i) \
;         __builtin_amdgcn_global_load_lds((const unsigned*)((const char*)(gbase) + (voff)[_i]), (LAS unsigned*)(lds + (bufoff) + ldsw + _i * 8192), 16, 0, 0); } while (0)
; #define PG8_LDA(dst, b, h) do { _Pragma("unroll") for (int m = 0; m < 4; ++m) _Pragma("unroll") for (int k = 0; k < 2; ++k) dst[m][k] = *(const LAS bf16x8*)(lds + PG8_SA(b, h) + aoff + m * 2048 + k * 1024); } while (0)
; #define PG8_LDB(dst, b, h) do { _Pragma("unroll") for (int n = 0; n < 2; ++n) _Pragma("unroll") for (int k = 0; k < 2; ++k) dst[n][k] = *(const LAS bf16x8*)(lds + PG8_SB(b, h) + boff + n * 2048 + k * 1024); } while (0)
; #define PG8_MMA(ai, bj, At, Bt) do { __builtin_amdgcn_s_setprio(1); _Pragma("unroll") for (int m = 0; m < 4; ++m) _Pragma("unroll") for (int n = 0; n < 2; ++n) _Pragma("unroll") for (int k = 0; k < 2; ++k) \
;         acc[ai][bj][m][n] = __builtin_amdgcn_mfma_f32_16x16x32_bf16(Bt[n][k], At[m][k], acc[ai][bj][m][n], 0, 0, 0); __builtin_amdgcn_s_setprio(0); } while (0)
; #define PG8_WAIT_V(n) asm volatile("s_waitcnt vmcnt(" #n ")" ::: "memory")
; #define PG8_WAIT_L(n) asm volatile("s_waitcnt lgkmcnt(" #n ")" ::: "memory")
; #define PG8_BAR __builtin_amdgcn_s_barrier()
; #define PG8_SCHED __builtin_amdgcn_sched_barrier(0)
; template <class Epi, bool ALIGN_EPI, class Hook = NoHook>
; __device__ __forceinline__ void gemm_phase(LAS unsigned char* lds, const Gemm g, const StaticOrder& S, const Epi& E, const Hook& HK = Hook()) {
;     ...
;             PG8_WAIT_V(8); PG8_WAIT_L(0); PG8_BAR; PG8_MMA(1, 0, At, B0); PG8_MMA(1, 1, At, B1); PG8_BAR; PG8_SCHED;
;             PG8_LDB(B0, 1, 0); PG8_LDB(B1, 1, 1); PG8_SCHED; PG8_LDA(At, 1, 0); PG8_STAGE(PG8_SA(0, 1), a2 + hstepA, voffA);
;             PG8_WAIT_V(8); PG8_WAIT_L(0); PG8_BAR; PG8_MMA(0, 0, At, B0); PG8_MMA(0, 1, At, B1); PG8_BAR; PG8_SCHED;
	s_setprio 1
	s_waitcnt lgkmcnt(0)
	v_mfma_f32_16x16x32_bf16 v[60:63], v[146:149], v[184:187], 0
	v_mfma_f32_16x16x32_bf16 v[56:59], v[160:163], v[184:187], 0
	v_mfma_f32_16x16x32_bf16 v[44:47], v[146:149], v[192:195], 0
	v_mfma_f32_16x16x32_bf16 v[40:43], v[160:163], v[192:195], 0
	v_mfma_f32_16x16x32_bf16 v[28:31], v[146:149], v[200:203], 0
	v_mfma_f32_16x16x32_bf16 v[24:27], v[160:163], v[200:203], 0
	v_mfma_f32_16x16x32_bf16 v[12:15], v[146:149], v[208:211], 0
	v_mfma_f32_16x16x32_bf16 v[8:11], v[160:163], v[208:211], 0
	v_mfma_f32_16x16x32_bf16 v[60:63], v[156:159], v[188:191], v[60:63]
	v_mfma_f32_16x16x32_bf16 v[56:59], v[164:167], v[188:191], v[56:59]
	v_mfma_f32_16x16x32_bf16 v[44:47], v[156:159], v[196:199], v[44:47]
	v_mfma_f32_16x16x32_bf16 v[40:43], v[164:167], v[196:199], v[40:43]
	v_mfma_f32_16x16x32_bf16 v[28:31], v[156:159], v[204:207], v[28:31]
	v_mfma_f32_16x16x32_bf16 v[24:27], v[164:167], v[204:207], v[24:27]
	v_mfma_f32_16x16x32_bf16 v[12:15], v[156:159], v[212:215], v[12:15]
	v_mfma_f32_16x16x32_bf16 v[8:11], v[164:167], v[212:215], v[8:11]
	s_setprio 0
	s_setprio 1
	v_mfma_f32_16x16x32_bf16 v[52:55], v[168:171], v[184:187], 0
	v_mfma_f32_16x16x32_bf16 v[48:51], v[176:179], v[184:187], 0
	v_mfma_f32_16x16x32_bf16 v[36:39], v[168:171], v[192:195], 0
	v_mfma_f32_16x16x32_bf16 v[32:35], v[176:179], v[192:195], 0
	v_mfma_f32_16x16x32_bf16 v[20:23], v[168:171], v[200:203], 0
	v_mfma_f32_16x16x32_bf16 v[16:19], v[176:179], v[200:203], 0
	v_mfma_f32_16x16x32_bf16 v[4:7], v[168:171], v[208:211], 0
	v_mfma_f32_16x16x32_bf16 v[0:3], v[176:179], v[208:211], 0
	v_mfma_f32_16x16x32_bf16 v[52:55], v[172:175], v[188:191], v[52:55]
	v_mfma_f32_16x16x32_bf16 v[48:51], v[180:183], v[188:191], v[48:51]
	v_mfma_f32_16x16x32_bf16 v[36:39], v[172:175], v[196:199], v[36:39]
	v_mfma_f32_16x16x32_bf16 v[32:35], v[180:183], v[196:199], v[32:35]
	v_mfma_f32_16x16x32_bf16 v[20:23], v[172:175], v[204:207], v[20:23]
	v_mfma_f32_16x16x32_bf16 v[16:19], v[180:183], v[204:207], v[16:19]
	v_mfma_f32_16x16x32_bf16 v[4:7], v[172:175], v[212:215], v[4:7]
	v_mfma_f32_16x16x32_bf16 v[0:3], v[180:183], v[212:215], v[0:3]
	s_setprio 0
	s_barrier
	s_add_i32 s58, 0, 0x18000
	v_add_u32_e32 v155, s58, v150
	s_add_i32 s59, 0, 0x1c000
	ds_read_b128 v[146:149], v155
	ds_read_b128 v[156:159], v155 offset:1024
	ds_read_b128 v[160:163], v155 offset:2048
	ds_read_b128 v[164:167], v155 offset:3072
	v_add_u32_e32 v155, s59, v150
	ds_read_b128 v[168:171], v155
	ds_read_b128 v[172:175], v155 offset:1024
	ds_read_b128 v[176:179], v155 offset:2048
	ds_read_b128 v[180:183], v155 offset:3072
	s_add_u32 s34, s36, 0x80000
	s_addc_u32 s35, s37, 0
	s_mov_b32 m0, s38
	v_lshl_add_u64 v[224:225], s[34:35], 0, v[134:135]
	ds_read_b128 v[184:187], v154 offset:32768
	ds_read_b128 v[188:191], v154 offset:33792
	ds_read_b128 v[192:195], v154 offset:34816
	ds_read_b128 v[196:199], v154 offset:35840
	ds_read_b128 v[200:203], v154 offset:36864
	ds_read_b128 v[204:207], v154 offset:37888
	ds_read_b128 v[208:211], v154 offset:38912
	ds_read_b128 v[212:215], v154 offset:39936
	global_load_lds_dwordx4 v[224:225], off
	v_lshl_add_u64 v[224:225], s[34:35], 0, v[130:131]
	s_mov_b32 m0, s39
	s_nop 0
	global_load_lds_dwordx4 v[224:225], off
	s_waitcnt vmcnt(8)
	s_waitcnt lgkmcnt(0)
	s_barrier
	s_setprio 1
	s_waitcnt lgkmcnt(0)
	v_mfma_f32_16x16x32_bf16 v[124:127], v[146:149], v[184:187], v[124:127]
	v_mfma_f32_16x16x32_bf16 v[120:123], v[160:163], v[184:187], v[120:123]
	v_mfma_f32_16x16x32_bf16 v[108:111], v[146:149], v[192:195], v[108:111]
	v_mfma_f32_16x16x32_bf16 v[104:107], v[160:163], v[192:195], v[104:107]
	v_mfma_f32_16x16x32_bf16 v[92:95], v[146:149], v[200:203], v[92:95]
	v_mfma_f32_16x16x32_bf16 v[88:91], v[160:163], v[200:203], v[88:91]
	v_mfma_f32_16x16x32_bf16 v[76:79], v[146:149], v[208:211], v[76:79]
	v_mfma_f32_16x16x32_bf16 v[72:75], v[160:163], v[208:211], v[72:75]
	v_mfma_f32_16x16x32_bf16 v[124:127], v[156:159], v[188:191], v[124:127]
	v_mfma_f32_16x16x32_bf16 v[120:123], v[164:167], v[188:191], v[120:123]
	v_mfma_f32_16x16x32_bf16 v[108:111], v[156:159], v[196:199], v[108:111]
	v_mfma_f32_16x16x32_bf16 v[104:107], v[164:167], v[196:199], v[104:107]
	v_mfma_f32_16x16x32_bf16 v[92:95], v[156:159], v[204:207], v[92:95]
	v_mfma_f32_16x16x32_bf16 v[88:91], v[164:167], v[204:207], v[88:91]
	v_mfma_f32_16x16x32_bf16 v[76:79], v[156:159], v[212:215], v[76:79]
	v_mfma_f32_16x16x32_bf16 v[72:75], v[164:167], v[212:215], v[72:75]
	s_setprio 0
	s_setprio 1
	v_mfma_f32_16x16x32_bf16 v[116:119], v[168:171], v[184:187], v[116:119]
	v_mfma_f32_16x16x32_bf16 v[112:115], v[176:179], v[184:187], v[112:115]
	v_mfma_f32_16x16x32_bf16 v[100:103], v[168:171], v[192:195], v[100:103]
	v_mfma_f32_16x16x32_bf16 v[96:99], v[176:179], v[192:195], v[96:99]
	v_mfma_f32_16x16x32_bf16 v[84:87], v[168:171], v[200:203], v[84:87]
	v_mfma_f32_16x16x32_bf16 v[80:83], v[176:179], v[200:203], v[80:83]
	v_mfma_f32_16x16x32_bf16 v[68:71], v[168:171], v[208:211], v[68:71]
	v_mfma_f32_16x16x32_bf16 v[64:67], v[176:179], v[208:211], v[64:67]
	v_mfma_f32_16x16x32_bf16 v[116:119], v[172:175], v[188:191], v[116:119]
	v_mfma_f32_16x16x32_bf16 v[112:115], v[180:183], v[188:191], v[112:115]
	v_mfma_f32_16x16x32_bf16 v[100:103], v[172:175], v[196:199], v[100:103]
	v_mfma_f32_16x16x32_bf16 v[96:99], v[180:183], v[196:199], v[96:99]
	v_mfma_f32_16x16x32_bf16 v[84:87], v[172:175], v[204:207], v[84:87]
	v_mfma_f32_16x16x32_bf16 v[80:83], v[180:183], v[204:207], v[80:83]
	v_mfma_f32_16x16x32_bf16 v[68:71], v[172:175], v[212:215], v[68:71]
	v_mfma_f32_16x16x32_bf16 v[64:67], v[180:183], v[212:215], v[64:67]
	s_setprio 0
	s_barrier
; #define PG8_STAGE(bufoff, gbase, voff) do { _Pragma("unroll") for (int _i = 0; _i < 2; ++_i) \
;         __builtin_amdgcn_global_load_lds((const unsigned*)((const char*)(gbase) + (voff)[_i]), (LAS unsigned*)(lds + (bufoff) + ldsw + _i * 8192), 16, 0, 0); } while (0)
; #define PG8_LDA(dst, b, h) do { _Pragma("unroll") for (int m = 0; m < 4; ++m) _Pragma("unroll") for (int k = 0; k < 2; ++k) dst[m][k] = *(const LAS bf16x8*)(lds + PG8_SA(b, h) + aoff + m * 2048 + k * 1024); } while (0)
; #define PG8_MMA(ai, bj, At, Bt) do { __builtin_amdgcn_s_setprio(1); _Pragma("unroll") for (int m = 0; m < 4; ++m) _Pragma("unroll") for (int n = 0; n < 2; ++n) _Pragma("unroll") for (int k = 0; k < 2; ++k) \
;         acc[ai][bj][m][n] = __builtin_amdgcn_mfma_f32_16x16x32_bf16(Bt[n][k], At[m][k], acc[ai][bj][m][n], 0, 0, 0); __builtin_amdgcn_s_setprio(0); } while (0)
; #define PG8_WAIT_V(n) asm volatile("s_waitcnt vmcnt(" #n ")" ::: "memory")
; #define PG8_WAIT_L(n) asm volatile("s_waitcnt lgkmcnt(" #n ")" ::: "memory")
; #define PG8_BAR __builtin_amdgcn_s_barrier()
; #define PG8_SCHED __builtin_amdgcn_sched_barrier(0)
; template <class Epi, bool ALIGN_EPI, class Hook = NoHook>
; __device__ __forceinline__ void gemm_phase(LAS unsigned char* lds, const Gemm g, const StaticOrder& S, const Epi& E, const Hook& HK = Hook()) {
;     ...
;             PG8_LDA(At, 1, 1); PG8_STAGE(PG8_SB(1, 0), b3, voffB); PG8_STAGE(PG8_SB(1, 1), b3 + hstepB, voffB); PG8_STAGE(PG8_SA(1, 0), a3, voffA);
;             PG8_WAIT_V(8); PG8_WAIT_L(0); PG8_BAR; PG8_MMA(1, 0, At, B0); PG8_MMA(1, 1, At, B1); PG8_BAR; PG8_SCHED;
	s_add_i32 s34, s58, s13
	v_lshl_add_u64 v[216:217], v[216:217], 0, s[8:9]
	s_mov_b32 m0, s34
	ds_read_b128 v[184:187], v154 offset:49152
	ds_read_b128 v[188:191], v154 offset:50176
	ds_read_b128 v[192:195], v154 offset:51200
	ds_read_b128 v[196:199], v154 offset:52224
	ds_read_b128 v[200:203], v154 offset:53248
	ds_read_b128 v[204:207], v154 offset:54272
	ds_read_b128 v[208:211], v154 offset:55296
	ds_read_b128 v[212:215], v154 offset:56320
	global_load_lds_dwordx4 v[216:217], off
	s_add_i32 m0, s34, 0x2000
	s_add_u32 s28, s28, 0x80080
	v_lshl_add_u64 v[216:217], v[218:219], 0, s[8:9]
	s_addc_u32 s29, s29, 0
	s_add_i32 s34, s59, s13
	global_load_lds_dwordx4 v[216:217], off
	v_lshl_add_u64 v[216:217], s[28:29], 0, v[132:133]
	s_mov_b32 m0, s34
	s_nop 0
	global_load_lds_dwordx4 v[216:217], off
	v_lshl_add_u64 v[216:217], s[28:29], 0, v[128:129]
	s_add_i32 m0, s34, 0x2000
	s_nop 0
	global_load_lds_dwordx4 v[216:217], off
	v_lshl_add_u64 v[216:217], v[220:221], 0, s[8:9]
	s_mov_b32 m0, s41
	s_nop 0
	global_load_lds_dwordx4 v[216:217], off
	v_lshl_add_u64 v[216:217], v[222:223], 0, s[8:9]
	s_mov_b32 m0, s42
	s_nop 0
	global_load_lds_dwordx4 v[216:217], off
	s_waitcnt vmcnt(8)
	s_waitcnt lgkmcnt(0)
	s_barrier
	s_setprio 1
	s_waitcnt lgkmcnt(0)
	v_mfma_f32_16x16x32_bf16 v[60:63], v[146:149], v[184:187], v[60:63]
	v_mfma_f32_16x16x32_bf16 v[56:59], v[160:163], v[184:187], v[56:59]
	v_mfma_f32_16x16x32_bf16 v[44:47], v[146:149], v[192:195], v[44:47]
	v_mfma_f32_16x16x32_bf16 v[40:43], v[160:163], v[192:195], v[40:43]
	v_mfma_f32_16x16x32_bf16 v[28:31], v[146:149], v[200:203], v[28:31]
	v_mfma_f32_16x16x32_bf16 v[24:27], v[160:163], v[200:203], v[24:27]
	v_mfma_f32_16x16x32_bf16 v[12:15], v[146:149], v[208:211], v[12:15]
	v_mfma_f32_16x16x32_bf16 v[8:11], v[160:163], v[208:211], v[8:11]
	v_mfma_f32_16x16x32_bf16 v[60:63], v[156:159], v[188:191], v[60:63]
	v_mfma_f32_16x16x32_bf16 v[56:59], v[164:167], v[188:191], v[56:59]
	v_mfma_f32_16x16x32_bf16 v[44:47], v[156:159], v[196:199], v[44:47]
	v_mfma_f32_16x16x32_bf16 v[40:43], v[164:167], v[196:199], v[40:43]
	v_mfma_f32_16x16x32_bf16 v[28:31], v[156:159], v[204:207], v[28:31]
	v_mfma_f32_16x16x32_bf16 v[24:27], v[164:167], v[204:207], v[24:27]
	v_mfma_f32_16x16x32_bf16 v[12:15], v[156:159], v[212:215], v[12:15]
	v_mfma_f32_16x16x32_bf16 v[8:11], v[164:167], v[212:215], v[8:11]
	s_setprio 0
	s_setprio 1
	v_mfma_f32_16x16x32_bf16 v[52:55], v[168:171], v[184:187], v[52:55]
	v_mfma_f32_16x16x32_bf16 v[48:51], v[176:179], v[184:187], v[48:51]
	v_mfma_f32_16x16x32_bf16 v[36:39], v[168:171], v[192:195], v[36:39]
	v_mfma_f32_16x16x32_bf16 v[32:35], v[176:179], v[192:195], v[32:35]
	v_mfma_f32_16x16x32_bf16 v[20:23], v[168:171], v[200:203], v[20:23]
	v_mfma_f32_16x16x32_bf16 v[16:19], v[176:179], v[200:203], v[16:19]
	v_mfma_f32_16x16x32_bf16 v[4:7], v[168:171], v[208:211], v[4:7]
	v_mfma_f32_16x16x32_bf16 v[0:3], v[176:179], v[208:211], v[0:3]
	v_mfma_f32_16x16x32_bf16 v[52:55], v[172:175], v[188:191], v[52:55]
	v_mfma_f32_16x16x32_bf16 v[48:51], v[180:183], v[188:191], v[48:51]
	v_mfma_f32_16x16x32_bf16 v[36:39], v[172:175], v[196:199], v[36:39]
	v_mfma_f32_16x16x32_bf16 v[32:35], v[180:183], v[196:199], v[32:35]
	v_mfma_f32_16x16x32_bf16 v[20:23], v[172:175], v[204:207], v[20:23]
	v_mfma_f32_16x16x32_bf16 v[16:19], v[180:183], v[204:207], v[16:19]
	v_mfma_f32_16x16x32_bf16 v[4:7], v[172:175], v[212:215], v[4:7]
	v_mfma_f32_16x16x32_bf16 v[0:3], v[180:183], v[212:215], v[0:3]
	s_setprio 0
	s_barrier
	s_add_i32 s57, s57, 2
	s_add_u32 s24, s24, 0x100
	s_addc_u32 s25, s25, 0
	s_add_u32 s55, s55, 0x100
	s_addc_u32 s56, s56, 0
	s_cmp_gt_u32 s57, 29

; #define PG8_STAGE(bufoff, gbase, voff) do { _Pragma("unroll") for (int _i = 0; _i < 2; ++_i) \
;         __builtin_amdgcn_global_load_lds((const unsigned*)((const char*)(gbase) + (voff)[_i]), (LAS unsigned*)(lds + (bufoff) + ldsw + _i * 8192), 16, 0, 0); } while (0)
; #define PG8_LDA(dst, b, h) do { _Pragma("unroll") for (int m = 0; m < 4; ++m) _Pragma("unroll") for (int k = 0; k < 2; ++k) dst[m][k] = *(const LAS bf16x8*)(lds + PG8_SA(b, h) + aoff + m * 2048 + k * 1024); } while (0)
; #define PG8_LDB(dst, b, h) do { _Pragma("unroll") for (int n = 0; n < 2; ++n) _Pragma("unroll") for (int k = 0; k < 2; ++k) dst[n][k] = *(const LAS bf16x8*)(lds + PG8_SB(b, h) + boff + n * 2048 + k * 1024); } while (0)
; #define PG8_MMA(ai, bj, At, Bt) do { __builtin_amdgcn_s_setprio(1); _Pragma("unroll") for (int m = 0; m < 4; ++m) _Pragma("unroll") for (int n = 0; n < 2; ++n) _Pragma("unroll") for (int k = 0; k < 2; ++k) \
;         acc[ai][bj][m][n] = __builtin_amdgcn_mfma_f32_16x16x32_bf16(Bt[n][k], At[m][k], acc[ai][bj][m][n], 0, 0, 0); __builtin_amdgcn_s_setprio(0); } while (0)
; #define PG8_WAIT_V(n) asm volatile("s_waitcnt vmcnt(" #n ")" ::: "memory")
; #define PG8_WAIT_L(n) asm volatile("s_waitcnt lgkmcnt(" #n ")" ::: "memory")
; #define PG8_BAR __builtin_amdgcn_s_barrier()
; #define PG8_SCHED __builtin_amdgcn_sched_barrier(0)
; template <class Epi, bool ALIGN_EPI, class Hook = NoHook>
; __device__ __forceinline__ void gemm_phase(LAS unsigned char* lds, const Gemm g, const StaticOrder& S, const Epi& E, const Hook& HK = Hook()) {
;     ...
;             const bool last = (t == nt - 2);
;             const char* a1 = cA + (size_t)(t + 1) * kstep;
;             const char* a2 = last ? nA : cA + (size_t)(t + 2) * kstep; const char* b2 = last ? nB : cB + (size_t)(t + 2) * kstep;
;             const char* a3 = a2 + kstep; const char* b3 = b2 + kstep;
;             PG8_LDB(B0, 0, 0); PG8_LDB(B1, 0, 1); PG8_SCHED; PG8_LDA(At, 0, 0); PG8_STAGE(PG8_SA(1, 1), a1 + hstepA, voffA);
;             PG8_WAIT_V(8); PG8_WAIT_L(0); PG8_BAR; PG8_MMA(0, 0, At, B0); PG8_MMA(0, 1, At, B1); PG8_BAR; PG8_SCHED;
;             PG8_LDA(At, 0, 1); PG8_STAGE(PG8_SB(0, 0), b2, voffB); PG8_STAGE(PG8_SB(0, 1), b2 + hstepB, voffB); PG8_STAGE(PG8_SA(0, 0), a2, voffA);
;             PG8_WAIT_V(8); PG8_WAIT_L(0); PG8_BAR; PG8_MMA(1, 0, At, B0); PG8_MMA(1, 1, At, B1); PG8_BAR; PG8_SCHED;
.LBB0_998:
	s_add_u32 s41, s16, 0x100
	s_addc_u32 s42, s17, 0
	s_mov_b32 s43, -2
	ds_read_b128 v[144:147], v153
	ds_read_b128 v[156:159], v153 offset:1024
	ds_read_b128 v[160:163], v153 offset:2048
	ds_read_b128 v[164:167], v153 offset:3072
	ds_read_b128 v[168:171], v154
	ds_read_b128 v[172:175], v154 offset:1024
	ds_read_b128 v[176:179], v154 offset:2048
	ds_read_b128 v[180:183], v154 offset:3072
	s_add_u32 s16, s14, 0x100
	s_addc_u32 s17, s15, 0
	s_cmpk_eq_i32 s43, 0x54
	s_cselect_b32 s21, s5, s17
	s_cselect_b32 s20, s4, s16
	s_cselect_b32 s19, s13, s42
	s_cselect_b32 s18, s12, s41
	v_lshl_add_u64 v[148:149], s[14:15], 0, v[136:137]
	s_add_i32 m0, s23, 0xc000
	ds_read_b128 v[184:187], v155
	ds_read_b128 v[188:191], v155 offset:1024
	ds_read_b128 v[192:195], v155 offset:2048
	ds_read_b128 v[196:199], v155 offset:3072
	ds_read_b128 v[200:203], v155 offset:4096
	ds_read_b128 v[204:207], v155 offset:5120
	ds_read_b128 v[208:211], v155 offset:6144
	ds_read_b128 v[212:215], v155 offset:7168
	global_load_lds_dwordx4 v[148:149], off
	v_lshl_add_u64 v[148:149], s[14:15], 0, v[138:139]
	s_add_i32 m0, s23, 0xe000
	s_nop 0
	global_load_lds_dwordx4 v[148:149], off
	s_waitcnt vmcnt(8)
	s_waitcnt lgkmcnt(0)
	s_barrier
	s_setprio 1
	s_waitcnt lgkmcnt(0)
	v_mfma_f32_16x16x32_bf16 v[124:127], v[144:147], v[184:187], 0
	v_mfma_f32_16x16x32_bf16 v[120:123], v[160:163], v[184:187], 0
	v_mfma_f32_16x16x32_bf16 v[112:115], v[144:147], v[192:195], 0
	v_mfma_f32_16x16x32_bf16 v[104:107], v[160:163], v[192:195], 0
	v_mfma_f32_16x16x32_bf16 v[96:99], v[144:147], v[200:203], 0
	v_mfma_f32_16x16x32_bf16 v[88:91], v[160:163], v[200:203], 0
	v_mfma_f32_16x16x32_bf16 v[80:83], v[144:147], v[208:211], 0
	v_mfma_f32_16x16x32_bf16 v[72:75], v[160:163], v[208:211], 0
	v_mfma_f32_16x16x32_bf16 v[124:127], v[156:159], v[188:191], v[124:127]
	v_mfma_f32_16x16x32_bf16 v[120:123], v[164:167], v[188:191], v[120:123]
	v_mfma_f32_16x16x32_bf16 v[112:115], v[156:159], v[196:199], v[112:115]
	v_mfma_f32_16x16x32_bf16 v[104:107], v[164:167], v[196:199], v[104:107]
	v_mfma_f32_16x16x32_bf16 v[96:99], v[156:159], v[204:207], v[96:99]
	v_mfma_f32_16x16x32_bf16 v[88:91], v[164:167], v[204:207], v[88:91]
	v_mfma_f32_16x16x32_bf16 v[80:83], v[156:159], v[212:215], v[80:83]
	v_mfma_f32_16x16x32_bf16 v[72:75], v[164:167], v[212:215], v[72:75]
	s_setprio 0
	s_setprio 1
	v_mfma_f32_16x16x32_bf16 v[116:119], v[168:171], v[184:187], 0
	v_mfma_f32_16x16x32_bf16 v[108:111], v[176:179], v[184:187], 0
	v_mfma_f32_16x16x32_bf16 v[100:103], v[168:171], v[192:195], 0
	v_mfma_f32_16x16x32_bf16 v[92:95], v[176:179], v[192:195], 0
	v_mfma_f32_16x16x32_bf16 v[84:87], v[168:171], v[200:203], 0
	v_mfma_f32_16x16x32_bf16 v[76:79], v[176:179], v[200:203], 0
	v_mfma_f32_16x16x32_bf16 v[68:71], v[168:171], v[208:211], 0
	v_mfma_f32_16x16x32_bf16 v[64:67], v[176:179], v[208:211], 0
	v_mfma_f32_16x16x32_bf16 v[116:119], v[172:175], v[188:191], v[116:119]
	v_mfma_f32_16x16x32_bf16 v[108:111], v[180:183], v[188:191], v[108:111]
	v_mfma_f32_16x16x32_bf16 v[100:103], v[172:175], v[196:199], v[100:103]
	v_mfma_f32_16x16x32_bf16 v[92:95], v[180:183], v[196:199], v[92:95]
	v_mfma_f32_16x16x32_bf16 v[84:87], v[172:175], v[204:207], v[84:87]
	v_mfma_f32_16x16x32_bf16 v[76:79], v[180:183], v[204:207], v[76:79]
	v_mfma_f32_16x16x32_bf16 v[68:71], v[172:175], v[212:215], v[68:71]
	v_mfma_f32_16x16x32_bf16 v[64:67], v[180:183], v[212:215], v[64:67]
	s_setprio 0
	s_barrier
	s_add_i32 s14, s33, s22
	v_lshl_add_u64 v[148:149], s[18:19], 0, v[130:131]
	s_mov_b32 m0, s14
	ds_read_b128 v[184:187], v155 offset:16384
	ds_read_b128 v[188:191], v155 offset:17408
	ds_read_b128 v[192:195], v155 offset:18432
	ds_read_b128 v[196:199], v155 offset:19456
	ds_read_b128 v[200:203], v155 offset:20480
	ds_read_b128 v[204:207], v155 offset:21504
	ds_read_b128 v[208:211], v155 offset:22528
	ds_read_b128 v[212:215], v155 offset:23552
	global_load_lds_dwordx4 v[148:149], off
	s_add_i32 m0, s14, 0x2000
	s_add_u32 s14, s18, 0x160000
	v_lshl_add_u64 v[216:217], s[18:19], 0, v[134:135]
	s_addc_u32 s15, s19, 0
	s_add_i32 s34, s36, s22
	global_load_lds_dwordx4 v[216:217], off
	v_lshl_add_u64 v[218:219], s[14:15], 0, v[130:131]
	s_mov_b32 m0, s34
	v_lshl_add_u64 v[220:221], s[20:21], 0, v[132:133]
	global_load_lds_dwordx4 v[218:219], off
	v_lshl_add_u64 v[218:219], s[14:15], 0, v[134:135]
	s_add_i32 m0, s34, 0x2000
	s_nop 0
	global_load_lds_dwordx4 v[218:219], off
	v_lshl_add_u64 v[218:219], s[20:21], 0, v[128:129]
	s_mov_b32 m0, s23
	s_nop 0
	global_load_lds_dwordx4 v[218:219], off
	s_mov_b32 m0, s24
	s_nop 0
	global_load_lds_dwordx4 v[220:221], off
	s_waitcnt vmcnt(8)
	s_waitcnt lgkmcnt(0)
	s_barrier
; #define PG8_STAGE(bufoff, gbase, voff) do { _Pragma("unroll") for (int _i = 0; _i < 2; ++_i) \
;         __builtin_amdgcn_global_load_lds((const unsigned*)((const char*)(gbase) + (voff)[_i]), (LAS unsigned*)(lds + (bufoff) + ldsw + _i * 8192), 16, 0, 0); } while (0)
; #define PG8_LDA(dst, b, h) do { _Pragma("unroll") for (int m = 0; m < 4; ++m) _Pragma("unroll") for (int k = 0; k < 2; ++k) dst[m][k] = *(const LAS bf16x8*)(lds + PG8_SA(b, h) + aoff + m * 2048 + k * 1024); } while (0)
; #define PG8_LDB(dst, b, h) do { _Pragma("unroll") for (int n = 0; n < 2; ++n) _Pragma("unroll") for (int k = 0; k < 2; ++k) dst[n][k] = *(const LAS bf16x8*)(lds + PG8_SB(b, h) + boff + n * 2048 + k * 1024); } while (0)
; #define PG8_MMA(ai, bj, At, Bt) do { __builtin_amdgcn_s_setprio(1); _Pragma("unroll") for (int m = 0; m < 4; ++m) _Pragma("unroll") for (int n = 0; n < 2; ++n) _Pragma("unroll") for (int k = 0; k < 2; ++k) \
;         acc[ai][bj][m][n] = __builtin_amdgcn_mfma_f32_16x16x32_bf16(Bt[n][k], At[m][k], acc[ai][bj][m][n], 0, 0, 0); __builtin_amdgcn_s_setprio(0); } while (0)
; #define PG8_WAIT_V(n) asm volatile("s_waitcnt vmcnt(" #n ")" ::: "memory")
; #define PG8_WAIT_L(n) asm volatile("s_waitcnt lgkmcnt(" #n ")" ::: "memory")
; #define PG8_BAR __builtin_amdgcn_s_barrier()
; #define PG8_SCHED __builtin_amdgcn_sched_barrier(0)
; template <class Epi, bool ALIGN_EPI, class Hook = NoHook>
; __device__ __forceinline__ void gemm_phase(LAS unsigned char* lds, const Gemm g, const StaticOrder& S, const Epi& E, const Hook& HK = Hook()) {
;     ...
;             PG8_WAIT_V(8); PG8_WAIT_L(0); PG8_BAR; PG8_MMA(1, 0, At, B0); PG8_MMA(1, 1, At, B1); PG8_BAR; PG8_SCHED;
;             PG8_LDB(B0, 1, 0); PG8_LDB(B1, 1, 1); PG8_SCHED; PG8_LDA(At, 1, 0); PG8_STAGE(PG8_SA(0, 1), a2 + hstepA, voffA);
;             PG8_WAIT_V(8); PG8_WAIT_L(0); PG8_BAR; PG8_MMA(0, 0, At, B0); PG8_MMA(0, 1, At, B1); PG8_BAR; PG8_SCHED;
	s_setprio 1
	s_waitcnt lgkmcnt(0)
	v_mfma_f32_16x16x32_bf16 v[60:63], v[144:147], v[184:187], 0
	v_mfma_f32_16x16x32_bf16 v[56:59], v[160:163], v[184:187], 0
	v_mfma_f32_16x16x32_bf16 v[48:51], v[144:147], v[192:195], 0
	v_mfma_f32_16x16x32_bf16 v[40:43], v[160:163], v[192:195], 0
	v_mfma_f32_16x16x32_bf16 v[32:35], v[144:147], v[200:203], 0
	v_mfma_f32_16x16x32_bf16 v[24:27], v[160:163], v[200:203], 0
	v_mfma_f32_16x16x32_bf16 v[16:19], v[144:147], v[208:211], 0
	v_mfma_f32_16x16x32_bf16 v[8:11], v[160:163], v[208:211], 0
	v_mfma_f32_16x16x32_bf16 v[60:63], v[156:159], v[188:191], v[60:63]
	v_mfma_f32_16x16x32_bf16 v[56:59], v[164:167], v[188:191], v[56:59]
	v_mfma_f32_16x16x32_bf16 v[48:51], v[156:159], v[196:199], v[48:51]
	v_mfma_f32_16x16x32_bf16 v[40:43], v[164:167], v[196:199], v[40:43]
	v_mfma_f32_16x16x32_bf16 v[32:35], v[156:159], v[204:207], v[32:35]
	v_mfma_f32_16x16x32_bf16 v[24:27], v[164:167], v[204:207], v[24:27]
	v_mfma_f32_16x16x32_bf16 v[16:19], v[156:159], v[212:215], v[16:19]
	v_mfma_f32_16x16x32_bf16 v[8:11], v[164:167], v[212:215], v[8:11]
	s_setprio 0
	s_setprio 1
	v_mfma_f32_16x16x32_bf16 v[52:55], v[168:171], v[184:187], 0
	v_mfma_f32_16x16x32_bf16 v[44:47], v[176:179], v[184:187], 0
	v_mfma_f32_16x16x32_bf16 v[36:39], v[168:171], v[192:195], 0
	v_mfma_f32_16x16x32_bf16 v[28:31], v[176:179], v[192:195], 0
	v_mfma_f32_16x16x32_bf16 v[20:23], v[168:171], v[200:203], 0
	v_mfma_f32_16x16x32_bf16 v[12:15], v[176:179], v[200:203], 0
	v_mfma_f32_16x16x32_bf16 v[4:7], v[168:171], v[208:211], 0
	v_mfma_f32_16x16x32_bf16 v[0:3], v[176:179], v[208:211], 0
	v_mfma_f32_16x16x32_bf16 v[52:55], v[172:175], v[188:191], v[52:55]
	v_mfma_f32_16x16x32_bf16 v[44:47], v[180:183], v[188:191], v[44:47]
	v_mfma_f32_16x16x32_bf16 v[36:39], v[172:175], v[196:199], v[36:39]
	v_mfma_f32_16x16x32_bf16 v[28:31], v[180:183], v[196:199], v[28:31]
	v_mfma_f32_16x16x32_bf16 v[20:23], v[172:175], v[204:207], v[20:23]
	v_mfma_f32_16x16x32_bf16 v[12:15], v[180:183], v[204:207], v[12:15]
	v_mfma_f32_16x16x32_bf16 v[4:7], v[172:175], v[212:215], v[4:7]
	v_mfma_f32_16x16x32_bf16 v[0:3], v[180:183], v[212:215], v[0:3]
	s_setprio 0
	s_barrier
	s_add_i32 s34, 0, 0x18000
	s_add_i32 s35, 0, 0x1c000
	v_add_u32_e32 v164, s34, v151
	v_add_u32_e32 v180, s35, v151
	ds_read_b128 v[144:147], v164
	ds_read_b128 v[156:159], v164 offset:1024
	ds_read_b128 v[160:163], v164 offset:2048
	ds_read_b128 v[164:167], v164 offset:3072
	ds_read_b128 v[168:171], v180
	ds_read_b128 v[172:175], v180 offset:1024
	ds_read_b128 v[176:179], v180 offset:2048
	ds_read_b128 v[180:183], v180 offset:3072
	s_add_u32 s14, s20, 0x160000
	s_addc_u32 s15, s21, 0
	s_mov_b32 m0, s25
	v_lshl_add_u64 v[222:223], s[14:15], 0, v[128:129]
	ds_read_b128 v[184:187], v155 offset:32768
	ds_read_b128 v[188:191], v155 offset:33792
	ds_read_b128 v[192:195], v155 offset:34816
	ds_read_b128 v[196:199], v155 offset:35840
	ds_read_b128 v[200:203], v155 offset:36864
	ds_read_b128 v[204:207], v155 offset:37888
	ds_read_b128 v[208:211], v155 offset:38912
	ds_read_b128 v[212:215], v155 offset:39936
	global_load_lds_dwordx4 v[222:223], off
	v_lshl_add_u64 v[222:223], s[14:15], 0, v[132:133]
	s_mov_b32 m0, s26
	s_nop 0
	global_load_lds_dwordx4 v[222:223], off
	s_waitcnt vmcnt(8)
	s_waitcnt lgkmcnt(0)
	s_barrier
	s_setprio 1
	s_waitcnt lgkmcnt(0)
	v_mfma_f32_16x16x32_bf16 v[124:127], v[144:147], v[184:187], v[124:127]
	v_mfma_f32_16x16x32_bf16 v[120:123], v[160:163], v[184:187], v[120:123]
	v_mfma_f32_16x16x32_bf16 v[112:115], v[144:147], v[192:195], v[112:115]
	v_mfma_f32_16x16x32_bf16 v[104:107], v[160:163], v[192:195], v[104:107]
	v_mfma_f32_16x16x32_bf16 v[96:99], v[144:147], v[200:203], v[96:99]
	v_mfma_f32_16x16x32_bf16 v[88:91], v[160:163], v[200:203], v[88:91]
	v_mfma_f32_16x16x32_bf16 v[80:83], v[144:147], v[208:211], v[80:83]
	v_mfma_f32_16x16x32_bf16 v[72:75], v[160:163], v[208:211], v[72:75]
	v_mfma_f32_16x16x32_bf16 v[124:127], v[156:159], v[188:191], v[124:127]
	v_mfma_f32_16x16x32_bf16 v[120:123], v[164:167], v[188:191], v[120:123]
	v_mfma_f32_16x16x32_bf16 v[112:115], v[156:159], v[196:199], v[112:115]
	v_mfma_f32_16x16x32_bf16 v[104:107], v[164:167], v[196:199], v[104:107]
	v_mfma_f32_16x16x32_bf16 v[96:99], v[156:159], v[204:207], v[96:99]
	v_mfma_f32_16x16x32_bf16 v[88:91], v[164:167], v[204:207], v[88:91]
	v_mfma_f32_16x16x32_bf16 v[80:83], v[156:159], v[212:215], v[80:83]
	v_mfma_f32_16x16x32_bf16 v[72:75], v[164:167], v[212:215], v[72:75]
	s_setprio 0
	s_setprio 1
	v_mfma_f32_16x16x32_bf16 v[116:119], v[168:171], v[184:187], v[116:119]
	v_mfma_f32_16x16x32_bf16 v[108:111], v[176:179], v[184:187], v[108:111]
	v_mfma_f32_16x16x32_bf16 v[100:103], v[168:171], v[192:195], v[100:103]
	v_mfma_f32_16x16x32_bf16 v[92:95], v[176:179], v[192:195], v[92:95]
	v_mfma_f32_16x16x32_bf16 v[84:87], v[168:171], v[200:203], v[84:87]
	v_mfma_f32_16x16x32_bf16 v[76:79], v[176:179], v[200:203], v[76:79]
	v_mfma_f32_16x16x32_bf16 v[68:71], v[168:171], v[208:211], v[68:71]
	v_mfma_f32_16x16x32_bf16 v[64:67], v[176:179], v[208:211], v[64:67]
	v_mfma_f32_16x16x32_bf16 v[116:119], v[172:175], v[188:191], v[116:119]
	v_mfma_f32_16x16x32_bf16 v[108:111], v[180:183], v[188:191], v[108:111]
	v_mfma_f32_16x16x32_bf16 v[100:103], v[172:175], v[196:199], v[100:103]
	v_mfma_f32_16x16x32_bf16 v[92:95], v[180:183], v[196:199], v[92:95]
	v_mfma_f32_16x16x32_bf16 v[84:87], v[172:175], v[204:207], v[84:87]
	v_mfma_f32_16x16x32_bf16 v[76:79], v[180:183], v[204:207], v[76:79]
	v_mfma_f32_16x16x32_bf16 v[68:71], v[172:175], v[212:215], v[68:71]
	v_mfma_f32_16x16x32_bf16 v[64:67], v[180:183], v[212:215], v[64:67]
	s_setprio 0
	s_barrier
; #define PG8_STAGE(bufoff, gbase, voff) do { _Pragma("unroll") for (int _i = 0; _i < 2; ++_i) \
;         __builtin_amdgcn_global_load_lds((const unsigned*)((const char*)(gbase) + (voff)[_i]), (LAS unsigned*)(lds + (bufoff) + ldsw + _i * 8192), 16, 0, 0); } while (0)
; #define PG8_LDA(dst, b, h) do { _Pragma("unroll") for (int m = 0; m < 4; ++m) _Pragma("unroll") for (int k = 0; k < 2; ++k) dst[m][k] = *(const LAS bf16x8*)(lds + PG8_SA(b, h) + aoff + m * 2048 + k * 1024); } while (0)
; #define PG8_MMA(ai, bj, At, Bt) do { __builtin_amdgcn_s_setprio(1); _Pragma("unroll") for (int m = 0; m < 4; ++m) _Pragma("unroll") for (int n = 0; n < 2; ++n) _Pragma("unroll") for (int k = 0; k < 2; ++k) \
;         acc[ai][bj][m][n] = __builtin_amdgcn_mfma_f32_16x16x32_bf16(Bt[n][k], At[m][k], acc[ai][bj][m][n], 0, 0, 0); __builtin_amdgcn_s_setprio(0); } while (0)
; #define PG8_WAIT_V(n) asm volatile("s_waitcnt vmcnt(" #n ")" ::: "memory")
; #define PG8_WAIT_L(n) asm volatile("s_waitcnt lgkmcnt(" #n ")" ::: "memory")
; #define PG8_BAR __builtin_amdgcn_s_barrier()
; #define PG8_SCHED __builtin_amdgcn_sched_barrier(0)
; template <class Epi, bool ALIGN_EPI, class Hook = NoHook>
; __device__ __forceinline__ void gemm_phase(LAS unsigned char* lds, const Gemm g, const StaticOrder& S, const Epi& E, const Hook& HK = Hook()) {
;     ...
;             PG8_LDA(At, 1, 1); PG8_STAGE(PG8_SB(1, 0), b3, voffB); PG8_STAGE(PG8_SB(1, 1), b3 + hstepB, voffB); PG8_STAGE(PG8_SA(1, 0), a3, voffA);
;             PG8_WAIT_V(8); PG8_WAIT_L(0); PG8_BAR; PG8_MMA(1, 0, At, B0); PG8_MMA(1, 1, At, B1); PG8_BAR; PG8_SCHED;
	s_add_i32 s14, s34, s22
	v_lshl_add_u64 v[148:149], v[148:149], 0, s[8:9]
	s_mov_b32 m0, s14
	ds_read_b128 v[184:187], v155 offset:49152
	ds_read_b128 v[188:191], v155 offset:50176
	ds_read_b128 v[192:195], v155 offset:51200
	ds_read_b128 v[196:199], v155 offset:52224
	ds_read_b128 v[200:203], v155 offset:53248
	ds_read_b128 v[204:207], v155 offset:54272
	ds_read_b128 v[208:211], v155 offset:55296
	ds_read_b128 v[212:215], v155 offset:56320
	global_load_lds_dwordx4 v[148:149], off
	s_add_i32 m0, s14, 0x2000
	s_add_u32 s14, s18, 0x160080
	v_lshl_add_u64 v[148:149], v[216:217], 0, s[8:9]
	s_addc_u32 s15, s19, 0
	s_add_i32 s18, s35, s22
	global_load_lds_dwordx4 v[148:149], off
	v_lshl_add_u64 v[148:149], s[14:15], 0, v[130:131]
	s_mov_b32 m0, s18
	s_nop 0
	global_load_lds_dwordx4 v[148:149], off
	v_lshl_add_u64 v[148:149], s[14:15], 0, v[134:135]
	s_add_i32 m0, s18, 0x2000
	s_nop 0
	global_load_lds_dwordx4 v[148:149], off
	v_lshl_add_u64 v[148:149], v[218:219], 0, s[8:9]
	s_mov_b32 m0, s28
	s_nop 0
	global_load_lds_dwordx4 v[148:149], off
	v_lshl_add_u64 v[148:149], v[220:221], 0, s[8:9]
	s_mov_b32 m0, s29
	s_nop 0
	global_load_lds_dwordx4 v[148:149], off
	s_waitcnt vmcnt(8)
	s_waitcnt lgkmcnt(0)
	s_barrier
	s_setprio 1
	s_waitcnt lgkmcnt(0)
	v_mfma_f32_16x16x32_bf16 v[60:63], v[144:147], v[184:187], v[60:63]
	v_mfma_f32_16x16x32_bf16 v[56:59], v[160:163], v[184:187], v[56:59]
	v_mfma_f32_16x16x32_bf16 v[48:51], v[144:147], v[192:195], v[48:51]
	v_mfma_f32_16x16x32_bf16 v[40:43], v[160:163], v[192:195], v[40:43]
	v_mfma_f32_16x16x32_bf16 v[32:35], v[144:147], v[200:203], v[32:35]
	v_mfma_f32_16x16x32_bf16 v[24:27], v[160:163], v[200:203], v[24:27]
	v_mfma_f32_16x16x32_bf16 v[16:19], v[144:147], v[208:211], v[16:19]
	v_mfma_f32_16x16x32_bf16 v[8:11], v[160:163], v[208:211], v[8:11]
	v_mfma_f32_16x16x32_bf16 v[60:63], v[156:159], v[188:191], v[60:63]
	v_mfma_f32_16x16x32_bf16 v[56:59], v[164:167], v[188:191], v[56:59]
	v_mfma_f32_16x16x32_bf16 v[48:51], v[156:159], v[196:199], v[48:51]
	v_mfma_f32_16x16x32_bf16 v[40:43], v[164:167], v[196:199], v[40:43]
	v_mfma_f32_16x16x32_bf16 v[32:35], v[156:159], v[204:207], v[32:35]
	v_mfma_f32_16x16x32_bf16 v[24:27], v[164:167], v[204:207], v[24:27]
	v_mfma_f32_16x16x32_bf16 v[16:19], v[156:159], v[212:215], v[16:19]
	v_mfma_f32_16x16x32_bf16 v[8:11], v[164:167], v[212:215], v[8:11]
	s_setprio 0
	s_setprio 1
	v_mfma_f32_16x16x32_bf16 v[52:55], v[168:171], v[184:187], v[52:55]
	v_mfma_f32_16x16x32_bf16 v[44:47], v[176:179], v[184:187], v[44:47]
	v_mfma_f32_16x16x32_bf16 v[36:39], v[168:171], v[192:195], v[36:39]
	v_mfma_f32_16x16x32_bf16 v[28:31], v[176:179], v[192:195], v[28:31]
	v_mfma_f32_16x16x32_bf16 v[20:23], v[168:171], v[200:203], v[20:23]
	v_mfma_f32_16x16x32_bf16 v[12:15], v[176:179], v[200:203], v[12:15]
	v_mfma_f32_16x16x32_bf16 v[4:7], v[168:171], v[208:211], v[4:7]
	v_mfma_f32_16x16x32_bf16 v[0:3], v[176:179], v[208:211], v[0:3]
	v_mfma_f32_16x16x32_bf16 v[52:55], v[172:175], v[188:191], v[52:55]
	v_mfma_f32_16x16x32_bf16 v[44:47], v[180:183], v[188:191], v[44:47]
	v_mfma_f32_16x16x32_bf16 v[36:39], v[172:175], v[196:199], v[36:39]
	v_mfma_f32_16x16x32_bf16 v[28:31], v[180:183], v[196:199], v[28:31]
	v_mfma_f32_16x16x32_bf16 v[20:23], v[172:175], v[204:207], v[20:23]
	v_mfma_f32_16x16x32_bf16 v[12:15], v[180:183], v[204:207], v[12:15]
	v_mfma_f32_16x16x32_bf16 v[4:7], v[172:175], v[212:215], v[4:7]
	v_mfma_f32_16x16x32_bf16 v[0:3], v[180:183], v[212:215], v[0:3]
	s_setprio 0
	s_barrier
	s_add_i32 s43, s43, 2
	s_add_u32 s41, s41, 0x100
	s_addc_u32 s42, s42, 0
	s_cmpk_gt_u32 s43, 0x55
	s_mov_b64 s[14:15], s[16:17]
